# dilated-attention units: Q/K/state/ymix accesses re-laid out through LDS so each global access touches whole rows (4x fewer cache-line touches); plus no-setprio GEMM loops
# speedup vs baseline: 1.0236x; 1.0156x over previous
.LBB0_314:
	s_mov_b64 exec, -1
	s_load_dwordx2 s[100:101], s[0:1], 0xf0
	s_mov_b32 s98, s97
	v_and_b32_e32 v128, 31, v206
	v_bfe_u32 v249, v206, 5, 1
	v_lshlrev_b32_e32 v129, 4, v249
	v_lshlrev_b32_e32 v250, 2, v249
	v_sub_u32_e32 v130, v128, v250
	v_mov_b32_e32 v131, 0xf149f2ca
	v_and_b32_e32 v133, 7, v206
	v_lshlrev_b32_e32 v133, 4, v133
	v_and_b32_e32 v134, 15, v206
	v_lshlrev_b32_e32 v134, 4, v134
	v_lshrrev_b32_e32 v251, 6, v206
	v_lshlrev_b32_e32 v251, 14, v251
	v_mul_u32_u24_e32 v252, 0x240, v249
	v_lshl_add_u32 v200, v128, 1, v252
	v_add_u32_e32 v200, v200, v251
	v_mul_u32_u24_e32 v252, 72, v128
	v_lshl_add_u32 v201, v249, 3, v252
	v_add_u32_e32 v201, v201, v251
	v_bfe_u32 v252, v206, 3, 3
	v_mul_u32_u24_e32 v252, 144, v252
	v_add3_u32 v202, v252, v133, v251
	v_add_u32_e32 v202, 4608, v202
	v_mul_u32_u24_e32 v252, 144, v128
	v_add3_u32 v203, v252, v129, v251
	v_add_u32_e32 v203, 4608, v203
	v_bfe_u32 v252, v206, 4, 2
	v_mul_u32_u24_e32 v252, 272, v252
	v_add3_u32 v204, v252, v134, v251
	v_add_u32_e32 v204, 4608, v204
	v_mul_u32_u24_e32 v252, 272, v128
	v_add3_u32 v205, v252, v129, v251
	v_add_u32_e32 v205, 4608, v205
	s_waitcnt lgkmcnt(0)
.Ldil_p0L0_loop:
	s_and_b32 s4, s98, 127
	s_mov_b32 s5, 0
	s_lshr_b32 s6, s98, 10
	s_and_b32 s7, s98, 0x380
	s_lshl_b32 s99, s6, 12
	s_add_u32 s8, s99, s5
	s_sub_u32 s9, 4, s4
	s_max_i32 s9, s9, 0
	s_lshl_b32 s4, s4, 5
	v_add_u32_e32 v135, s4, v128
	s_lshl_b32 s99, s8, 10
	s_add_u32 s99, s99, s7
	s_add_u32 s64, s99, 0x16000000
	s_add_u32 s64, s100, s64
	s_addc_u32 s65, s101, 0
	s_add_u32 s72, s64, 0x2000000
	s_addc_u32 s73, s65, 0
	s_add_u32 s52, s72, 0x2000000
	s_addc_u32 s53, s73, 0
	s_add_u32 s66, s64, 0x2000
	s_addc_u32 s67, s65, 0
	s_add_u32 s74, s72, 0x2000
	s_addc_u32 s75, s73, 0
	s_add_u32 s68, s66, 0x2000
	s_addc_u32 s69, s67, 0
	s_add_u32 s76, s74, 0x2000
	s_addc_u32 s77, s75, 0
	s_add_u32 s70, s68, 0x2000
	s_addc_u32 s71, s69, 0
	s_add_u32 s78, s76, 0x2000
	s_addc_u32 s79, s77, 0
	v_bfe_u32 v249, v206, 3, 3
	v_add_u32_e32 v249, s4, v249
	v_lshl_add_u32 v250, v249, 10, v133
	global_load_dwordx4 v[152:155], v250, s[64:65]
	global_load_dwordx4 v[156:159], v250, s[66:67]
	global_load_dwordx4 v[160:163], v250, s[68:69]
	global_load_dwordx4 v[164:167], v250, s[70:71]
	s_max_u32 s99, s9, 0
	s_lshl_b32 s99, s99, 5
	s_addk_i32 s99, 0xff80
	v_add_u32_e32 v250, s99, v249
	v_lshl_add_u32 v250, v250, 10, v133
	global_load_dwordx4 v[0:3], v250, s[72:73]
	global_load_dwordx4 v[4:7], v250, s[74:75]
	global_load_dwordx4 v[8:11], v250, s[76:77]
	global_load_dwordx4 v[12:15], v250, s[78:79]
	s_max_u32 s99, s9, 1
	s_lshl_b32 s99, s99, 5
	s_addk_i32 s99, 0xff80
	v_add_u32_e32 v250, s99, v249
	v_lshl_add_u32 v250, v250, 10, v133
	global_load_dwordx4 v[16:19], v250, s[72:73]
	global_load_dwordx4 v[20:23], v250, s[74:75]
	global_load_dwordx4 v[24:27], v250, s[76:77]
	global_load_dwordx4 v[28:31], v250, s[78:79]
	s_max_u32 s99, s9, 2
	s_lshl_b32 s99, s99, 5
	s_addk_i32 s99, 0xff80
	v_add_u32_e32 v250, s99, v249
	v_lshl_add_u32 v250, v250, 10, v133
	global_load_dwordx4 v[32:35], v250, s[72:73]
	global_load_dwordx4 v[36:39], v250, s[74:75]
	global_load_dwordx4 v[40:43], v250, s[76:77]
	global_load_dwordx4 v[44:47], v250, s[78:79]
	s_max_u32 s99, s9, 3
	s_lshl_b32 s99, s99, 5
	s_addk_i32 s99, 0xff80
	v_add_u32_e32 v250, s99, v249
	v_lshl_add_u32 v250, v250, 10, v133
	global_load_dwordx4 v[48:51], v250, s[72:73]
	global_load_dwordx4 v[52:55], v250, s[74:75]
	global_load_dwordx4 v[56:59], v250, s[76:77]
	global_load_dwordx4 v[60:63], v250, s[78:79]
	s_max_u32 s99, s9, 4
	s_lshl_b32 s99, s99, 5
	s_addk_i32 s99, 0xff80
	v_add_u32_e32 v250, s99, v249
	v_lshl_add_u32 v250, v250, 10, v133
	global_load_dwordx4 v[64:67], v250, s[72:73]
	global_load_dwordx4 v[68:71], v250, s[74:75]
	global_load_dwordx4 v[72:75], v250, s[76:77]
	global_load_dwordx4 v[76:79], v250, s[78:79]
	s_lshl_b32 s99, s8, 5
	s_lshr_b32 s58, s7, 5
	s_add_u32 s99, s99, s58
	s_add_u32 s99, s99, 0x400000
	s_add_u32 s58, s100, s99
	s_addc_u32 s59, s101, 0
	s_add_u32 s60, s58, 0x100000
	s_addc_u32 s61, s59, 0
	v_lshlrev_b32_e32 v240, 5, v135
	s_lshl_b32 s99, s8, 11
	s_lshl_b32 s56, s7, 1
	s_add_u32 s99, s99, s56
	s_add_u32 s99, s99, 0x8000000
	s_add_u32 s56, s100, s99
	s_addc_u32 s57, s101, 0
	v_bfe_u32 v251, v206, 4, 2
	v_add_u32_e32 v251, s4, v251
	v_lshl_add_u32 v241, v251, 11, v134
	v_mov_b32_e32 v244, v131
	v_mov_b32_e32 v245, 0
	v_mov_b32_e32 v208, 0
	v_mov_b32_e32 v224, 0
	v_mov_b32_e32 v209, 0
	v_mov_b32_e32 v225, 0
	v_mov_b32_e32 v210, 0
	v_mov_b32_e32 v226, 0
	v_mov_b32_e32 v211, 0
	v_mov_b32_e32 v227, 0
	v_mov_b32_e32 v212, 0
	v_mov_b32_e32 v228, 0
	v_mov_b32_e32 v213, 0
	v_mov_b32_e32 v229, 0
	v_mov_b32_e32 v214, 0
	v_mov_b32_e32 v230, 0
	v_mov_b32_e32 v215, 0
	v_mov_b32_e32 v231, 0
	v_mov_b32_e32 v216, 0
	v_mov_b32_e32 v232, 0
	v_mov_b32_e32 v217, 0
	v_mov_b32_e32 v233, 0
	v_mov_b32_e32 v218, 0
	v_mov_b32_e32 v234, 0
	v_mov_b32_e32 v219, 0
	v_mov_b32_e32 v235, 0
	v_mov_b32_e32 v220, 0
	v_mov_b32_e32 v236, 0
	v_mov_b32_e32 v221, 0
	v_mov_b32_e32 v237, 0
	v_mov_b32_e32 v222, 0
	v_mov_b32_e32 v238, 0
	v_mov_b32_e32 v223, 0
	v_mov_b32_e32 v239, 0
	v_mov_b32_e32 v243, v131
	s_waitcnt vmcnt(20)
	ds_write_b128 v202, v[152:155]
	ds_write_b128 v202, v[156:159] offset:1152
	ds_write_b128 v202, v[160:163] offset:2304
	ds_write_b128 v202, v[164:167] offset:3456
	s_waitcnt lgkmcnt(0)
	ds_read_b128 v[136:139], v203
	ds_read_b128 v[140:143], v203 offset:32
	ds_read_b128 v[144:147], v203 offset:64
	ds_read_b128 v[148:151], v203 offset:96
	s_cmp_gt_u32 s9, 0
	s_cbranch_scc1 .Ldil_p0L0_kskip0
	s_waitcnt vmcnt(16)
	s_waitcnt lgkmcnt(0)
	ds_write_b128 v202, v[0:3]
	ds_write_b128 v202, v[4:7] offset:1152
	ds_write_b128 v202, v[8:11] offset:2304
	ds_write_b128 v202, v[12:15] offset:3456
	s_waitcnt lgkmcnt(0)
	s_max_u32 s99, s9, 0
	s_lshl_b32 s99, s99, 5
	s_addk_i32 s99, 0xff80
	v_add_u32_e32 v250, s99, v135
	v_lshl_add_u32 v250, v250, 10, v129
	global_load_dwordx4 v[0:3], v250, s[52:53]
	global_load_dwordx4 v[4:7], v250, s[52:53] offset:32
	global_load_dwordx4 v[8:11], v250, s[52:53] offset:64
	global_load_dwordx4 v[12:15], v250, s[52:53] offset:96
	ds_read_b128 v[152:155], v203
	ds_read_b128 v[156:159], v203 offset:32
	ds_read_b128 v[160:163], v203 offset:64
	ds_read_b128 v[164:167], v203 offset:96
	s_waitcnt lgkmcnt(0)
	v_mfma_f32_32x32x16_bf16 v[80:95], v[152:155], v[136:139], 0
	v_mfma_f32_32x32x16_bf16 v[80:95], v[156:159], v[140:143], v[80:95]
	v_mfma_f32_32x32x16_bf16 v[80:95], v[160:163], v[144:147], v[80:95]
	v_mfma_f32_32x32x16_bf16 v[80:95], v[164:167], v[148:151], v[80:95]
	s_nop 7
	s_nop 3
	v_cmp_gt_i32_e64 s[34:35], v130, 0
	v_cmp_gt_i32_e64 s[36:37], v130, 1
	v_cmp_gt_i32_e64 s[38:39], v130, 2
	v_cmp_gt_i32_e64 s[40:41], v130, 3
	v_cndmask_b32_e64 v80, v80, v131, s[34:35]
	v_cndmask_b32_e64 v81, v81, v131, s[36:37]
	v_cndmask_b32_e64 v82, v82, v131, s[38:39]
	v_cndmask_b32_e64 v83, v83, v131, s[40:41]
	v_cmp_gt_i32_e64 s[34:35], v130, 8
	v_cmp_gt_i32_e64 s[36:37], v130, 9
	v_cmp_gt_i32_e64 s[38:39], v130, 10
	v_cmp_gt_i32_e64 s[40:41], v130, 11
	v_cndmask_b32_e64 v84, v84, v131, s[34:35]
	v_cndmask_b32_e64 v85, v85, v131, s[36:37]
	v_cndmask_b32_e64 v86, v86, v131, s[38:39]
	v_cndmask_b32_e64 v87, v87, v131, s[40:41]
	v_cmp_gt_i32_e64 s[34:35], v130, 16
	v_cmp_gt_i32_e64 s[36:37], v130, 17
	v_cmp_gt_i32_e64 s[38:39], v130, 18
	v_cmp_gt_i32_e64 s[40:41], v130, 19
	v_cndmask_b32_e64 v88, v88, v131, s[34:35]
	v_cndmask_b32_e64 v89, v89, v131, s[36:37]
	v_cndmask_b32_e64 v90, v90, v131, s[38:39]
	v_cndmask_b32_e64 v91, v91, v131, s[40:41]
	v_cmp_gt_i32_e64 s[34:35], v130, 24
	v_cmp_gt_i32_e64 s[36:37], v130, 25
	v_cmp_gt_i32_e64 s[38:39], v130, 26
	v_cmp_gt_i32_e64 s[40:41], v130, 27
	v_cndmask_b32_e64 v92, v92, v131, s[34:35]
	v_cndmask_b32_e64 v93, v93, v131, s[36:37]
	v_cndmask_b32_e64 v94, v94, v131, s[38:39]
	v_cndmask_b32_e64 v95, v95, v131, s[40:41]
	v_max3_f32 v243, v243, v80, v81
	v_max3_f32 v243, v243, v82, v83
	v_max3_f32 v243, v243, v84, v85
	v_max3_f32 v243, v243, v86, v87
	v_max3_f32 v243, v243, v88, v89
	v_max3_f32 v243, v243, v90, v91
	v_max3_f32 v243, v243, v92, v93
	v_max3_f32 v243, v243, v94, v95
	s_branch .Ldil_p0L0_kdone0
.Ldil_p0L0_kskip0:
	s_max_u32 s99, s9, 0
	s_lshl_b32 s99, s99, 5
	s_addk_i32 s99, 0xff80
	v_add_u32_e32 v250, s99, v135
	v_lshl_add_u32 v250, v250, 10, v129
	global_load_dwordx4 v[0:3], v250, s[52:53]
	global_load_dwordx4 v[4:7], v250, s[52:53] offset:32
	global_load_dwordx4 v[8:11], v250, s[52:53] offset:64
	global_load_dwordx4 v[12:15], v250, s[52:53] offset:96
.Ldil_p0L0_kdone0:
	s_cmp_gt_u32 s9, 1
	s_cbranch_scc1 .Ldil_p0L0_kskip1
	s_waitcnt vmcnt(16)
	s_waitcnt lgkmcnt(0)
	ds_write_b128 v202, v[16:19]
	ds_write_b128 v202, v[20:23] offset:1152
	ds_write_b128 v202, v[24:27] offset:2304
	ds_write_b128 v202, v[28:31] offset:3456
	s_waitcnt lgkmcnt(0)
	s_max_u32 s99, s9, 1
	s_lshl_b32 s99, s99, 5
	s_addk_i32 s99, 0xff80
	v_add_u32_e32 v250, s99, v135
	v_lshl_add_u32 v250, v250, 10, v129
	global_load_dwordx4 v[16:19], v250, s[52:53]
	global_load_dwordx4 v[20:23], v250, s[52:53] offset:32
	global_load_dwordx4 v[24:27], v250, s[52:53] offset:64
	global_load_dwordx4 v[28:31], v250, s[52:53] offset:96
	ds_read_b128 v[152:155], v203
	ds_read_b128 v[156:159], v203 offset:32
	ds_read_b128 v[160:163], v203 offset:64
	ds_read_b128 v[164:167], v203 offset:96
	s_waitcnt lgkmcnt(0)
	v_mfma_f32_32x32x16_bf16 v[96:111], v[152:155], v[136:139], 0
	v_mfma_f32_32x32x16_bf16 v[96:111], v[156:159], v[140:143], v[96:111]
	v_mfma_f32_32x32x16_bf16 v[96:111], v[160:163], v[144:147], v[96:111]
	v_mfma_f32_32x32x16_bf16 v[96:111], v[164:167], v[148:151], v[96:111]
	s_nop 7
	s_nop 3
	v_max3_f32 v243, v243, v96, v97
	v_max3_f32 v243, v243, v98, v99
	v_max3_f32 v243, v243, v100, v101
	v_max3_f32 v243, v243, v102, v103
	v_max3_f32 v243, v243, v104, v105
	v_max3_f32 v243, v243, v106, v107
	v_max3_f32 v243, v243, v108, v109
	v_max3_f32 v243, v243, v110, v111
	s_branch .Ldil_p0L0_kdone1
.Ldil_p0L0_kskip1:
	s_max_u32 s99, s9, 1
	s_lshl_b32 s99, s99, 5
	s_addk_i32 s99, 0xff80
	v_add_u32_e32 v250, s99, v135
	v_lshl_add_u32 v250, v250, 10, v129
	global_load_dwordx4 v[16:19], v250, s[52:53]
	global_load_dwordx4 v[20:23], v250, s[52:53] offset:32
	global_load_dwordx4 v[24:27], v250, s[52:53] offset:64
	global_load_dwordx4 v[28:31], v250, s[52:53] offset:96
.Ldil_p0L0_kdone1:
	s_cmp_gt_u32 s9, 2
	s_cbranch_scc1 .Ldil_p0L0_kskip2
	s_waitcnt vmcnt(16)
	s_waitcnt lgkmcnt(0)
	ds_write_b128 v202, v[32:35]
	ds_write_b128 v202, v[36:39] offset:1152
	ds_write_b128 v202, v[40:43] offset:2304
	ds_write_b128 v202, v[44:47] offset:3456
	s_waitcnt lgkmcnt(0)
	s_max_u32 s99, s9, 2
	s_lshl_b32 s99, s99, 5
	s_addk_i32 s99, 0xff80
	v_add_u32_e32 v250, s99, v135
	v_lshl_add_u32 v250, v250, 10, v129
	global_load_dwordx4 v[32:35], v250, s[52:53]
	global_load_dwordx4 v[36:39], v250, s[52:53] offset:32
	global_load_dwordx4 v[40:43], v250, s[52:53] offset:64
	global_load_dwordx4 v[44:47], v250, s[52:53] offset:96
	ds_read_b128 v[152:155], v203
	ds_read_b128 v[156:159], v203 offset:32
	ds_read_b128 v[160:163], v203 offset:64
	ds_read_b128 v[164:167], v203 offset:96
	s_waitcnt lgkmcnt(0)
	v_mfma_f32_32x32x16_bf16 v[112:127], v[152:155], v[136:139], 0
	v_mfma_f32_32x32x16_bf16 v[112:127], v[156:159], v[140:143], v[112:127]
	v_mfma_f32_32x32x16_bf16 v[112:127], v[160:163], v[144:147], v[112:127]
	v_mfma_f32_32x32x16_bf16 v[112:127], v[164:167], v[148:151], v[112:127]
	s_nop 7
	s_nop 3
	v_max3_f32 v243, v243, v112, v113
	v_max3_f32 v243, v243, v114, v115
	v_max3_f32 v243, v243, v116, v117
	v_max3_f32 v243, v243, v118, v119
	v_max3_f32 v243, v243, v120, v121
	v_max3_f32 v243, v243, v122, v123
	v_max3_f32 v243, v243, v124, v125
	v_max3_f32 v243, v243, v126, v127
	s_branch .Ldil_p0L0_kdone2
.Ldil_p0L0_kskip2:
	s_max_u32 s99, s9, 2
	s_lshl_b32 s99, s99, 5
	s_addk_i32 s99, 0xff80
	v_add_u32_e32 v250, s99, v135
	v_lshl_add_u32 v250, v250, 10, v129
	global_load_dwordx4 v[32:35], v250, s[52:53]
	global_load_dwordx4 v[36:39], v250, s[52:53] offset:32
	global_load_dwordx4 v[40:43], v250, s[52:53] offset:64
	global_load_dwordx4 v[44:47], v250, s[52:53] offset:96
.Ldil_p0L0_kdone2:
	s_cmp_gt_u32 s9, 3
	s_cbranch_scc1 .Ldil_p0L0_kskip3
	s_waitcnt vmcnt(16)
	s_waitcnt lgkmcnt(0)
	ds_write_b128 v202, v[48:51]
	ds_write_b128 v202, v[52:55] offset:1152
	ds_write_b128 v202, v[56:59] offset:2304
	ds_write_b128 v202, v[60:63] offset:3456
	s_waitcnt lgkmcnt(0)
	s_max_u32 s99, s9, 3
	s_lshl_b32 s99, s99, 5
	s_addk_i32 s99, 0xff80
	v_add_u32_e32 v250, s99, v135
	v_lshl_add_u32 v250, v250, 10, v129
	global_load_dwordx4 v[48:51], v250, s[52:53]
	global_load_dwordx4 v[52:55], v250, s[52:53] offset:32
	global_load_dwordx4 v[56:59], v250, s[52:53] offset:64
	global_load_dwordx4 v[60:63], v250, s[52:53] offset:96
	ds_read_b128 v[152:155], v203
	ds_read_b128 v[156:159], v203 offset:32
	ds_read_b128 v[160:163], v203 offset:64
	ds_read_b128 v[164:167], v203 offset:96
	s_waitcnt lgkmcnt(0)
	v_mfma_f32_32x32x16_bf16 v[168:183], v[152:155], v[136:139], 0
	v_mfma_f32_32x32x16_bf16 v[168:183], v[156:159], v[140:143], v[168:183]
	v_mfma_f32_32x32x16_bf16 v[168:183], v[160:163], v[144:147], v[168:183]
	v_mfma_f32_32x32x16_bf16 v[168:183], v[164:167], v[148:151], v[168:183]
	s_nop 7
	s_nop 3
	v_max3_f32 v243, v243, v168, v169
	v_max3_f32 v243, v243, v170, v171
	v_max3_f32 v243, v243, v172, v173
	v_max3_f32 v243, v243, v174, v175
	v_max3_f32 v243, v243, v176, v177
	v_max3_f32 v243, v243, v178, v179
	v_max3_f32 v243, v243, v180, v181
	v_max3_f32 v243, v243, v182, v183
	s_branch .Ldil_p0L0_kdone3
.Ldil_p0L0_kskip3:
	s_max_u32 s99, s9, 3
	s_lshl_b32 s99, s99, 5
	s_addk_i32 s99, 0xff80
	v_add_u32_e32 v250, s99, v135
	v_lshl_add_u32 v250, v250, 10, v129
	global_load_dwordx4 v[48:51], v250, s[52:53]
	global_load_dwordx4 v[52:55], v250, s[52:53] offset:32
	global_load_dwordx4 v[56:59], v250, s[52:53] offset:64
	global_load_dwordx4 v[60:63], v250, s[52:53] offset:96
.Ldil_p0L0_kdone3:
	s_waitcnt vmcnt(16)
	s_waitcnt lgkmcnt(0)
	ds_write_b128 v202, v[64:67]
	ds_write_b128 v202, v[68:71] offset:1152
	ds_write_b128 v202, v[72:75] offset:2304
	ds_write_b128 v202, v[76:79] offset:3456
	s_waitcnt lgkmcnt(0)
	s_max_u32 s99, s9, 4
	s_lshl_b32 s99, s99, 5
	s_addk_i32 s99, 0xff80
	v_add_u32_e32 v250, s99, v135
	v_lshl_add_u32 v250, v250, 10, v129
	global_load_dwordx4 v[64:67], v250, s[52:53]
	global_load_dwordx4 v[68:71], v250, s[52:53] offset:32
	global_load_dwordx4 v[72:75], v250, s[52:53] offset:64
	global_load_dwordx4 v[76:79], v250, s[52:53] offset:96
	ds_read_b128 v[152:155], v203
	ds_read_b128 v[156:159], v203 offset:32
	ds_read_b128 v[160:163], v203 offset:64
	ds_read_b128 v[164:167], v203 offset:96
	s_waitcnt lgkmcnt(0)
	v_mfma_f32_32x32x16_bf16 v[184:199], v[152:155], v[136:139], 0
	v_mfma_f32_32x32x16_bf16 v[184:199], v[156:159], v[140:143], v[184:199]
	v_mfma_f32_32x32x16_bf16 v[184:199], v[160:163], v[144:147], v[184:199]
	v_mfma_f32_32x32x16_bf16 v[184:199], v[164:167], v[148:151], v[184:199]
	s_nop 7
	s_nop 3
	v_cmp_lt_i32_e64 s[34:35], v130, 0
	v_cmp_lt_i32_e64 s[36:37], v130, 1
	v_cmp_lt_i32_e64 s[38:39], v130, 2
	v_cmp_lt_i32_e64 s[40:41], v130, 3
	v_cndmask_b32_e64 v184, v184, v131, s[34:35]
	v_cndmask_b32_e64 v185, v185, v131, s[36:37]
	v_cndmask_b32_e64 v186, v186, v131, s[38:39]
	v_cndmask_b32_e64 v187, v187, v131, s[40:41]
	v_cmp_lt_i32_e64 s[34:35], v130, 8
	v_cmp_lt_i32_e64 s[36:37], v130, 9
	v_cmp_lt_i32_e64 s[38:39], v130, 10
	v_cmp_lt_i32_e64 s[40:41], v130, 11
	v_cndmask_b32_e64 v188, v188, v131, s[34:35]
	v_cndmask_b32_e64 v189, v189, v131, s[36:37]
	v_cndmask_b32_e64 v190, v190, v131, s[38:39]
	v_cndmask_b32_e64 v191, v191, v131, s[40:41]
	v_cmp_lt_i32_e64 s[34:35], v130, 16
	v_cmp_lt_i32_e64 s[36:37], v130, 17
	v_cmp_lt_i32_e64 s[38:39], v130, 18
	v_cmp_lt_i32_e64 s[40:41], v130, 19
	v_cndmask_b32_e64 v192, v192, v131, s[34:35]
	v_cndmask_b32_e64 v193, v193, v131, s[36:37]
	v_cndmask_b32_e64 v194, v194, v131, s[38:39]
	v_cndmask_b32_e64 v195, v195, v131, s[40:41]
	v_cmp_lt_i32_e64 s[34:35], v130, 24
	v_cmp_lt_i32_e64 s[36:37], v130, 25
	v_cmp_lt_i32_e64 s[38:39], v130, 26
	v_cmp_lt_i32_e64 s[40:41], v130, 27
	v_cndmask_b32_e64 v196, v196, v131, s[34:35]
	v_cndmask_b32_e64 v197, v197, v131, s[36:37]
	v_cndmask_b32_e64 v198, v198, v131, s[38:39]
	v_cndmask_b32_e64 v199, v199, v131, s[40:41]
	v_max3_f32 v243, v243, v184, v185
	v_max3_f32 v243, v243, v186, v187
	v_max3_f32 v243, v243, v188, v189
	v_max3_f32 v243, v243, v190, v191
	v_max3_f32 v243, v243, v192, v193
	v_max3_f32 v243, v243, v194, v195
	v_max3_f32 v243, v243, v196, v197
	v_max3_f32 v243, v243, v198, v199
	v_mov_b32_e32 v249, v243
	s_nop 1
	v_permlane32_swap_b32_e32 v243, v249
	s_waitcnt vmcnt(20)
	v_max3_f32 v246, v244, v243, v249
	v_sub_f32_e32 v247, v244, v246
	v_exp_f32_e32 v247, v247
	v_mov_b32_e32 v248, 0
	s_cmp_gt_u32 s9, 0
	s_cbranch_scc1 .Ldil_p0L0_eskip0
	v_sub_f32_e32 v80, v80, v246
	v_sub_f32_e32 v81, v81, v246
	v_exp_f32_e32 v80, v80
	v_sub_f32_e32 v82, v82, v246
	v_exp_f32_e32 v81, v81
	v_add_f32_e32 v248, v248, v80
	v_sub_f32_e32 v83, v83, v246
	v_exp_f32_e32 v82, v82
	v_add_f32_e32 v248, v248, v81
	v_sub_f32_e32 v84, v84, v246
	v_exp_f32_e32 v83, v83
	v_add_f32_e32 v248, v248, v82
	v_sub_f32_e32 v85, v85, v246
	v_exp_f32_e32 v84, v84
	v_add_f32_e32 v248, v248, v83
	v_sub_f32_e32 v86, v86, v246
	v_exp_f32_e32 v85, v85
	v_add_f32_e32 v248, v248, v84
	v_sub_f32_e32 v87, v87, v246
	v_exp_f32_e32 v86, v86
	v_add_f32_e32 v248, v248, v85
	v_sub_f32_e32 v88, v88, v246
	v_exp_f32_e32 v87, v87
	v_add_f32_e32 v248, v248, v86
	v_sub_f32_e32 v89, v89, v246
	v_exp_f32_e32 v88, v88
	v_add_f32_e32 v248, v248, v87
	v_sub_f32_e32 v90, v90, v246
	v_exp_f32_e32 v89, v89
	v_add_f32_e32 v248, v248, v88
	v_sub_f32_e32 v91, v91, v246
	v_exp_f32_e32 v90, v90
	v_add_f32_e32 v248, v248, v89
	v_sub_f32_e32 v92, v92, v246
	v_exp_f32_e32 v91, v91
	v_add_f32_e32 v248, v248, v90
	v_sub_f32_e32 v93, v93, v246
	v_exp_f32_e32 v92, v92
	v_add_f32_e32 v248, v248, v91
	v_sub_f32_e32 v94, v94, v246
	v_exp_f32_e32 v93, v93
	v_add_f32_e32 v248, v248, v92
	v_sub_f32_e32 v95, v95, v246
	v_exp_f32_e32 v94, v94
	v_add_f32_e32 v248, v248, v93
	v_exp_f32_e32 v95, v95
	v_add_f32_e32 v248, v248, v94
	s_nop 0
	v_add_f32_e32 v248, v248, v95
.Ldil_p0L0_eskip0:
	s_cmp_gt_u32 s9, 1
	s_cbranch_scc1 .Ldil_p0L0_eskip1
	v_sub_f32_e32 v96, v96, v246
	v_sub_f32_e32 v97, v97, v246
	v_exp_f32_e32 v96, v96
	v_sub_f32_e32 v98, v98, v246
	v_exp_f32_e32 v97, v97
	v_add_f32_e32 v248, v248, v96
	v_sub_f32_e32 v99, v99, v246
	v_exp_f32_e32 v98, v98
	v_add_f32_e32 v248, v248, v97
	v_sub_f32_e32 v100, v100, v246
	v_exp_f32_e32 v99, v99
	v_add_f32_e32 v248, v248, v98
	v_sub_f32_e32 v101, v101, v246
	v_exp_f32_e32 v100, v100
	v_add_f32_e32 v248, v248, v99
	v_sub_f32_e32 v102, v102, v246
	v_exp_f32_e32 v101, v101
	v_add_f32_e32 v248, v248, v100
	v_sub_f32_e32 v103, v103, v246
	v_exp_f32_e32 v102, v102
	v_add_f32_e32 v248, v248, v101
	v_sub_f32_e32 v104, v104, v246
	v_exp_f32_e32 v103, v103
	v_add_f32_e32 v248, v248, v102
	v_sub_f32_e32 v105, v105, v246
	v_exp_f32_e32 v104, v104
	v_add_f32_e32 v248, v248, v103
	v_sub_f32_e32 v106, v106, v246
	v_exp_f32_e32 v105, v105
	v_add_f32_e32 v248, v248, v104
	v_sub_f32_e32 v107, v107, v246
	v_exp_f32_e32 v106, v106
	v_add_f32_e32 v248, v248, v105
	v_sub_f32_e32 v108, v108, v246
	v_exp_f32_e32 v107, v107
	v_add_f32_e32 v248, v248, v106
	v_sub_f32_e32 v109, v109, v246
	v_exp_f32_e32 v108, v108
	v_add_f32_e32 v248, v248, v107
	v_sub_f32_e32 v110, v110, v246
	v_exp_f32_e32 v109, v109
	v_add_f32_e32 v248, v248, v108
	v_sub_f32_e32 v111, v111, v246
	v_exp_f32_e32 v110, v110
	v_add_f32_e32 v248, v248, v109
	v_exp_f32_e32 v111, v111
	v_add_f32_e32 v248, v248, v110
	s_nop 0
	v_add_f32_e32 v248, v248, v111
.Ldil_p0L0_eskip1:
	s_cmp_gt_u32 s9, 2
	s_cbranch_scc1 .Ldil_p0L0_eskip2
	v_sub_f32_e32 v112, v112, v246
	v_sub_f32_e32 v113, v113, v246
	v_exp_f32_e32 v112, v112
	v_sub_f32_e32 v114, v114, v246
	v_exp_f32_e32 v113, v113
	v_add_f32_e32 v248, v248, v112
	v_sub_f32_e32 v115, v115, v246
	v_exp_f32_e32 v114, v114
	v_add_f32_e32 v248, v248, v113
	v_sub_f32_e32 v116, v116, v246
	v_exp_f32_e32 v115, v115
	v_add_f32_e32 v248, v248, v114
	v_sub_f32_e32 v117, v117, v246
	v_exp_f32_e32 v116, v116
	v_add_f32_e32 v248, v248, v115
	v_sub_f32_e32 v118, v118, v246
	v_exp_f32_e32 v117, v117
	v_add_f32_e32 v248, v248, v116
	v_sub_f32_e32 v119, v119, v246
	v_exp_f32_e32 v118, v118
	v_add_f32_e32 v248, v248, v117
	v_sub_f32_e32 v120, v120, v246
	v_exp_f32_e32 v119, v119
	v_add_f32_e32 v248, v248, v118
	v_sub_f32_e32 v121, v121, v246
	v_exp_f32_e32 v120, v120
	v_add_f32_e32 v248, v248, v119
	v_sub_f32_e32 v122, v122, v246
	v_exp_f32_e32 v121, v121
	v_add_f32_e32 v248, v248, v120
	v_sub_f32_e32 v123, v123, v246
	v_exp_f32_e32 v122, v122
	v_add_f32_e32 v248, v248, v121
	v_sub_f32_e32 v124, v124, v246
	v_exp_f32_e32 v123, v123
	v_add_f32_e32 v248, v248, v122
	v_sub_f32_e32 v125, v125, v246
	v_exp_f32_e32 v124, v124
	v_add_f32_e32 v248, v248, v123
	v_sub_f32_e32 v126, v126, v246
	v_exp_f32_e32 v125, v125
	v_add_f32_e32 v248, v248, v124
	v_sub_f32_e32 v127, v127, v246
	v_exp_f32_e32 v126, v126
	v_add_f32_e32 v248, v248, v125
	v_exp_f32_e32 v127, v127
	v_add_f32_e32 v248, v248, v126
	s_nop 0
	v_add_f32_e32 v248, v248, v127
.Ldil_p0L0_eskip2:
	s_cmp_gt_u32 s9, 3
	s_cbranch_scc1 .Ldil_p0L0_eskip3
	v_sub_f32_e32 v168, v168, v246
	v_sub_f32_e32 v169, v169, v246
	v_exp_f32_e32 v168, v168
	v_sub_f32_e32 v170, v170, v246
	v_exp_f32_e32 v169, v169
	v_add_f32_e32 v248, v248, v168
	v_sub_f32_e32 v171, v171, v246
	v_exp_f32_e32 v170, v170
	v_add_f32_e32 v248, v248, v169
	v_sub_f32_e32 v172, v172, v246
	v_exp_f32_e32 v171, v171
	v_add_f32_e32 v248, v248, v170
	v_sub_f32_e32 v173, v173, v246
	v_exp_f32_e32 v172, v172
	v_add_f32_e32 v248, v248, v171
	v_sub_f32_e32 v174, v174, v246
	v_exp_f32_e32 v173, v173
	v_add_f32_e32 v248, v248, v172
	v_sub_f32_e32 v175, v175, v246
	v_exp_f32_e32 v174, v174
	v_add_f32_e32 v248, v248, v173
	v_sub_f32_e32 v176, v176, v246
	v_exp_f32_e32 v175, v175
	v_add_f32_e32 v248, v248, v174
	v_sub_f32_e32 v177, v177, v246
	v_exp_f32_e32 v176, v176
	v_add_f32_e32 v248, v248, v175
	v_sub_f32_e32 v178, v178, v246
	v_exp_f32_e32 v177, v177
	v_add_f32_e32 v248, v248, v176
	v_sub_f32_e32 v179, v179, v246
	v_exp_f32_e32 v178, v178
	v_add_f32_e32 v248, v248, v177
	v_sub_f32_e32 v180, v180, v246
	v_exp_f32_e32 v179, v179
	v_add_f32_e32 v248, v248, v178
	v_sub_f32_e32 v181, v181, v246
	v_exp_f32_e32 v180, v180
	v_add_f32_e32 v248, v248, v179
	v_sub_f32_e32 v182, v182, v246
	v_exp_f32_e32 v181, v181
	v_add_f32_e32 v248, v248, v180
	v_sub_f32_e32 v183, v183, v246
	v_exp_f32_e32 v182, v182
	v_add_f32_e32 v248, v248, v181
	v_exp_f32_e32 v183, v183
	v_add_f32_e32 v248, v248, v182
	s_nop 0
	v_add_f32_e32 v248, v248, v183
.Ldil_p0L0_eskip3:
	v_sub_f32_e32 v184, v184, v246
	v_sub_f32_e32 v185, v185, v246
	v_exp_f32_e32 v184, v184
	v_sub_f32_e32 v186, v186, v246
	v_exp_f32_e32 v185, v185
	v_add_f32_e32 v248, v248, v184
	v_sub_f32_e32 v187, v187, v246
	v_exp_f32_e32 v186, v186
	v_add_f32_e32 v248, v248, v185
	v_sub_f32_e32 v188, v188, v246
	v_exp_f32_e32 v187, v187
	v_add_f32_e32 v248, v248, v186
	v_sub_f32_e32 v189, v189, v246
	v_exp_f32_e32 v188, v188
	v_add_f32_e32 v248, v248, v187
	v_sub_f32_e32 v190, v190, v246
	v_exp_f32_e32 v189, v189
	v_add_f32_e32 v248, v248, v188
	v_sub_f32_e32 v191, v191, v246
	v_exp_f32_e32 v190, v190
	v_add_f32_e32 v248, v248, v189
	v_sub_f32_e32 v192, v192, v246
	v_exp_f32_e32 v191, v191
	v_add_f32_e32 v248, v248, v190
	v_sub_f32_e32 v193, v193, v246
	v_exp_f32_e32 v192, v192
	v_add_f32_e32 v248, v248, v191
	v_sub_f32_e32 v194, v194, v246
	v_exp_f32_e32 v193, v193
	v_add_f32_e32 v248, v248, v192
	v_sub_f32_e32 v195, v195, v246
	v_exp_f32_e32 v194, v194
	v_add_f32_e32 v248, v248, v193
	v_sub_f32_e32 v196, v196, v246
	v_exp_f32_e32 v195, v195
	v_add_f32_e32 v248, v248, v194
	v_sub_f32_e32 v197, v197, v246
	v_exp_f32_e32 v196, v196
	v_add_f32_e32 v248, v248, v195
	v_sub_f32_e32 v198, v198, v246
	v_exp_f32_e32 v197, v197
	v_add_f32_e32 v248, v248, v196
	v_sub_f32_e32 v199, v199, v246
	v_exp_f32_e32 v198, v198
	v_add_f32_e32 v248, v248, v197
	v_exp_f32_e32 v199, v199
	v_add_f32_e32 v248, v248, v198
	s_nop 0
	v_add_f32_e32 v248, v248, v199
	v_mov_b32_e32 v249, v248
	s_nop 1
	v_permlane32_swap_b32_e32 v248, v249
	s_nop 1
	v_add_f32_e32 v248, v248, v249
	v_fmac_f32_e32 v248, v245, v247
	v_add_u32_e32 v251, 2304, v201
	s_cmp_gt_u32 s9, 0
	s_cbranch_scc1 .Ldil_p0L0_pskip0
	s_waitcnt vmcnt(16)
	ds_write_b16 v200, v0
	ds_write_b16_d16_hi v200, v0 offset:72
	ds_write_b16 v200, v1 offset:144
	ds_write_b16_d16_hi v200, v1 offset:216
	ds_write_b16 v200, v2 offset:288
	ds_write_b16_d16_hi v200, v2 offset:360
	ds_write_b16 v200, v3 offset:432
	ds_write_b16_d16_hi v200, v3 offset:504
	ds_write_b16 v200, v4 offset:1152
	ds_write_b16_d16_hi v200, v4 offset:1224
	ds_write_b16 v200, v5 offset:1296
	ds_write_b16_d16_hi v200, v5 offset:1368
	ds_write_b16 v200, v6 offset:1440
	ds_write_b16_d16_hi v200, v6 offset:1512
	ds_write_b16 v200, v7 offset:1584
	ds_write_b16_d16_hi v200, v7 offset:1656
	ds_write_b16 v200, v8 offset:2304
	ds_write_b16_d16_hi v200, v8 offset:2376
	ds_write_b16 v200, v9 offset:2448
	ds_write_b16_d16_hi v200, v9 offset:2520
	ds_write_b16 v200, v10 offset:2592
	ds_write_b16_d16_hi v200, v10 offset:2664
	ds_write_b16 v200, v11 offset:2736
	ds_write_b16_d16_hi v200, v11 offset:2808
	ds_write_b16 v200, v12 offset:3456
	ds_write_b16_d16_hi v200, v12 offset:3528
	ds_write_b16 v200, v13 offset:3600
	ds_write_b16_d16_hi v200, v13 offset:3672
	ds_write_b16 v200, v14 offset:3744
	ds_write_b16_d16_hi v200, v14 offset:3816
	ds_write_b16 v200, v15 offset:3888
	ds_write_b16_d16_hi v200, v15 offset:3960
	v_cvt_pk_bf16_f32 v136, v80, v81
	v_cvt_pk_bf16_f32 v137, v82, v83
	v_cvt_pk_bf16_f32 v138, v84, v85
	v_cvt_pk_bf16_f32 v139, v86, v87
	v_cvt_pk_bf16_f32 v140, v88, v89
	v_cvt_pk_bf16_f32 v141, v90, v91
	v_cvt_pk_bf16_f32 v142, v92, v93
	v_cvt_pk_bf16_f32 v143, v94, v95
	s_waitcnt lgkmcnt(0)
	ds_read2_b64 v[152:155], v201 offset0:0 offset1:2
	ds_read2_b64 v[156:159], v251 offset0:0 offset1:2
	ds_read2_b64 v[160:163], v201 offset0:4 offset1:6
	ds_read2_b64 v[164:167], v251 offset0:4 offset1:6
	s_waitcnt lgkmcnt(0)
	v_mfma_f32_32x32x16_bf16 v[208:223], v[152:155], v[136:139], v[208:223]
	v_mfma_f32_32x32x16_bf16 v[224:239], v[156:159], v[136:139], v[224:239]
	v_mfma_f32_32x32x16_bf16 v[208:223], v[160:163], v[140:143], v[208:223]
	v_mfma_f32_32x32x16_bf16 v[224:239], v[164:167], v[140:143], v[224:239]
.Ldil_p0L0_pskip0:
	s_cmp_gt_u32 s9, 1
	s_cbranch_scc1 .Ldil_p0L0_pskip1
	s_waitcnt vmcnt(12)
	ds_write_b16 v200, v16
	ds_write_b16_d16_hi v200, v16 offset:72
	ds_write_b16 v200, v17 offset:144
	ds_write_b16_d16_hi v200, v17 offset:216
	ds_write_b16 v200, v18 offset:288
	ds_write_b16_d16_hi v200, v18 offset:360
	ds_write_b16 v200, v19 offset:432
	ds_write_b16_d16_hi v200, v19 offset:504
	ds_write_b16 v200, v20 offset:1152
	ds_write_b16_d16_hi v200, v20 offset:1224
	ds_write_b16 v200, v21 offset:1296
	ds_write_b16_d16_hi v200, v21 offset:1368
	ds_write_b16 v200, v22 offset:1440
	ds_write_b16_d16_hi v200, v22 offset:1512
	ds_write_b16 v200, v23 offset:1584
	ds_write_b16_d16_hi v200, v23 offset:1656
	ds_write_b16 v200, v24 offset:2304
	ds_write_b16_d16_hi v200, v24 offset:2376
	ds_write_b16 v200, v25 offset:2448
	ds_write_b16_d16_hi v200, v25 offset:2520
	ds_write_b16 v200, v26 offset:2592
	ds_write_b16_d16_hi v200, v26 offset:2664
	ds_write_b16 v200, v27 offset:2736
	ds_write_b16_d16_hi v200, v27 offset:2808
	ds_write_b16 v200, v28 offset:3456
	ds_write_b16_d16_hi v200, v28 offset:3528
	ds_write_b16 v200, v29 offset:3600
	ds_write_b16_d16_hi v200, v29 offset:3672
	ds_write_b16 v200, v30 offset:3744
	ds_write_b16_d16_hi v200, v30 offset:3816
	ds_write_b16 v200, v31 offset:3888
	ds_write_b16_d16_hi v200, v31 offset:3960
	v_cvt_pk_bf16_f32 v136, v96, v97
	v_cvt_pk_bf16_f32 v137, v98, v99
	v_cvt_pk_bf16_f32 v138, v100, v101
	v_cvt_pk_bf16_f32 v139, v102, v103
	v_cvt_pk_bf16_f32 v140, v104, v105
	v_cvt_pk_bf16_f32 v141, v106, v107
	v_cvt_pk_bf16_f32 v142, v108, v109
	v_cvt_pk_bf16_f32 v143, v110, v111
	s_waitcnt lgkmcnt(0)
	ds_read2_b64 v[152:155], v201 offset0:0 offset1:2
	ds_read2_b64 v[156:159], v251 offset0:0 offset1:2
	ds_read2_b64 v[160:163], v201 offset0:4 offset1:6
	ds_read2_b64 v[164:167], v251 offset0:4 offset1:6
	s_waitcnt lgkmcnt(0)
	v_mfma_f32_32x32x16_bf16 v[208:223], v[152:155], v[136:139], v[208:223]
	v_mfma_f32_32x32x16_bf16 v[224:239], v[156:159], v[136:139], v[224:239]
	v_mfma_f32_32x32x16_bf16 v[208:223], v[160:163], v[140:143], v[208:223]
	v_mfma_f32_32x32x16_bf16 v[224:239], v[164:167], v[140:143], v[224:239]
.Ldil_p0L0_pskip1:
	s_cmp_gt_u32 s9, 2
	s_cbranch_scc1 .Ldil_p0L0_pskip2
	s_waitcnt vmcnt(8)
	ds_write_b16 v200, v32
	ds_write_b16_d16_hi v200, v32 offset:72
	ds_write_b16 v200, v33 offset:144
	ds_write_b16_d16_hi v200, v33 offset:216
	ds_write_b16 v200, v34 offset:288
	ds_write_b16_d16_hi v200, v34 offset:360
	ds_write_b16 v200, v35 offset:432
	ds_write_b16_d16_hi v200, v35 offset:504
	ds_write_b16 v200, v36 offset:1152
	ds_write_b16_d16_hi v200, v36 offset:1224
	ds_write_b16 v200, v37 offset:1296
	ds_write_b16_d16_hi v200, v37 offset:1368
	ds_write_b16 v200, v38 offset:1440
	ds_write_b16_d16_hi v200, v38 offset:1512
	ds_write_b16 v200, v39 offset:1584
	ds_write_b16_d16_hi v200, v39 offset:1656
	ds_write_b16 v200, v40 offset:2304
	ds_write_b16_d16_hi v200, v40 offset:2376
	ds_write_b16 v200, v41 offset:2448
	ds_write_b16_d16_hi v200, v41 offset:2520
	ds_write_b16 v200, v42 offset:2592
	ds_write_b16_d16_hi v200, v42 offset:2664
	ds_write_b16 v200, v43 offset:2736
	ds_write_b16_d16_hi v200, v43 offset:2808
	ds_write_b16 v200, v44 offset:3456
	ds_write_b16_d16_hi v200, v44 offset:3528
	ds_write_b16 v200, v45 offset:3600
	ds_write_b16_d16_hi v200, v45 offset:3672
	ds_write_b16 v200, v46 offset:3744
	ds_write_b16_d16_hi v200, v46 offset:3816
	ds_write_b16 v200, v47 offset:3888
	ds_write_b16_d16_hi v200, v47 offset:3960
	v_cvt_pk_bf16_f32 v136, v112, v113
	v_cvt_pk_bf16_f32 v137, v114, v115
	v_cvt_pk_bf16_f32 v138, v116, v117
	v_cvt_pk_bf16_f32 v139, v118, v119
	v_cvt_pk_bf16_f32 v140, v120, v121
	v_cvt_pk_bf16_f32 v141, v122, v123
	v_cvt_pk_bf16_f32 v142, v124, v125
	v_cvt_pk_bf16_f32 v143, v126, v127
	s_waitcnt lgkmcnt(0)
	ds_read2_b64 v[152:155], v201 offset0:0 offset1:2
	ds_read2_b64 v[156:159], v251 offset0:0 offset1:2
	ds_read2_b64 v[160:163], v201 offset0:4 offset1:6
	ds_read2_b64 v[164:167], v251 offset0:4 offset1:6
	s_waitcnt lgkmcnt(0)
	v_mfma_f32_32x32x16_bf16 v[208:223], v[152:155], v[136:139], v[208:223]
	v_mfma_f32_32x32x16_bf16 v[224:239], v[156:159], v[136:139], v[224:239]
	v_mfma_f32_32x32x16_bf16 v[208:223], v[160:163], v[140:143], v[208:223]
	v_mfma_f32_32x32x16_bf16 v[224:239], v[164:167], v[140:143], v[224:239]
.Ldil_p0L0_pskip2:
	s_cmp_gt_u32 s9, 3
	s_cbranch_scc1 .Ldil_p0L0_pskip3
	s_waitcnt vmcnt(4)
	ds_write_b16 v200, v48
	ds_write_b16_d16_hi v200, v48 offset:72
	ds_write_b16 v200, v49 offset:144
	ds_write_b16_d16_hi v200, v49 offset:216
	ds_write_b16 v200, v50 offset:288
	ds_write_b16_d16_hi v200, v50 offset:360
	ds_write_b16 v200, v51 offset:432
	ds_write_b16_d16_hi v200, v51 offset:504
	ds_write_b16 v200, v52 offset:1152
	ds_write_b16_d16_hi v200, v52 offset:1224
	ds_write_b16 v200, v53 offset:1296
	ds_write_b16_d16_hi v200, v53 offset:1368
	ds_write_b16 v200, v54 offset:1440
	ds_write_b16_d16_hi v200, v54 offset:1512
	ds_write_b16 v200, v55 offset:1584
	ds_write_b16_d16_hi v200, v55 offset:1656
	ds_write_b16 v200, v56 offset:2304
	ds_write_b16_d16_hi v200, v56 offset:2376
	ds_write_b16 v200, v57 offset:2448
	ds_write_b16_d16_hi v200, v57 offset:2520
	ds_write_b16 v200, v58 offset:2592
	ds_write_b16_d16_hi v200, v58 offset:2664
	ds_write_b16 v200, v59 offset:2736
	ds_write_b16_d16_hi v200, v59 offset:2808
	ds_write_b16 v200, v60 offset:3456
	ds_write_b16_d16_hi v200, v60 offset:3528
	ds_write_b16 v200, v61 offset:3600
	ds_write_b16_d16_hi v200, v61 offset:3672
	ds_write_b16 v200, v62 offset:3744
	ds_write_b16_d16_hi v200, v62 offset:3816
	ds_write_b16 v200, v63 offset:3888
	ds_write_b16_d16_hi v200, v63 offset:3960
	v_cvt_pk_bf16_f32 v136, v168, v169
	v_cvt_pk_bf16_f32 v137, v170, v171
	v_cvt_pk_bf16_f32 v138, v172, v173
	v_cvt_pk_bf16_f32 v139, v174, v175
	v_cvt_pk_bf16_f32 v140, v176, v177
	v_cvt_pk_bf16_f32 v141, v178, v179
	v_cvt_pk_bf16_f32 v142, v180, v181
	v_cvt_pk_bf16_f32 v143, v182, v183
	s_waitcnt lgkmcnt(0)
	ds_read2_b64 v[152:155], v201 offset0:0 offset1:2
	ds_read2_b64 v[156:159], v251 offset0:0 offset1:2
	ds_read2_b64 v[160:163], v201 offset0:4 offset1:6
	ds_read2_b64 v[164:167], v251 offset0:4 offset1:6
	s_waitcnt lgkmcnt(0)
	v_mfma_f32_32x32x16_bf16 v[208:223], v[152:155], v[136:139], v[208:223]
	v_mfma_f32_32x32x16_bf16 v[224:239], v[156:159], v[136:139], v[224:239]
	v_mfma_f32_32x32x16_bf16 v[208:223], v[160:163], v[140:143], v[208:223]
	v_mfma_f32_32x32x16_bf16 v[224:239], v[164:167], v[140:143], v[224:239]
.Ldil_p0L0_pskip3:
	s_waitcnt vmcnt(0)
	ds_write_b16 v200, v64
	ds_write_b16_d16_hi v200, v64 offset:72
	ds_write_b16 v200, v65 offset:144
	ds_write_b16_d16_hi v200, v65 offset:216
	ds_write_b16 v200, v66 offset:288
	ds_write_b16_d16_hi v200, v66 offset:360
	ds_write_b16 v200, v67 offset:432
	ds_write_b16_d16_hi v200, v67 offset:504
	ds_write_b16 v200, v68 offset:1152
	ds_write_b16_d16_hi v200, v68 offset:1224
	ds_write_b16 v200, v69 offset:1296
	ds_write_b16_d16_hi v200, v69 offset:1368
	ds_write_b16 v200, v70 offset:1440
	ds_write_b16_d16_hi v200, v70 offset:1512
	ds_write_b16 v200, v71 offset:1584
	ds_write_b16_d16_hi v200, v71 offset:1656
	ds_write_b16 v200, v72 offset:2304
	ds_write_b16_d16_hi v200, v72 offset:2376
	ds_write_b16 v200, v73 offset:2448
	ds_write_b16_d16_hi v200, v73 offset:2520
	ds_write_b16 v200, v74 offset:2592
	ds_write_b16_d16_hi v200, v74 offset:2664
	ds_write_b16 v200, v75 offset:2736
	ds_write_b16_d16_hi v200, v75 offset:2808
	ds_write_b16 v200, v76 offset:3456
	ds_write_b16_d16_hi v200, v76 offset:3528
	ds_write_b16 v200, v77 offset:3600
	ds_write_b16_d16_hi v200, v77 offset:3672
	ds_write_b16 v200, v78 offset:3744
	ds_write_b16_d16_hi v200, v78 offset:3816
	ds_write_b16 v200, v79 offset:3888
	ds_write_b16_d16_hi v200, v79 offset:3960
	v_cvt_pk_bf16_f32 v136, v184, v185
	v_cvt_pk_bf16_f32 v137, v186, v187
	v_cvt_pk_bf16_f32 v138, v188, v189
	v_cvt_pk_bf16_f32 v139, v190, v191
	v_cvt_pk_bf16_f32 v140, v192, v193
	v_cvt_pk_bf16_f32 v141, v194, v195
	v_cvt_pk_bf16_f32 v142, v196, v197
	v_cvt_pk_bf16_f32 v143, v198, v199
	s_waitcnt lgkmcnt(0)
	ds_read2_b64 v[152:155], v201 offset0:0 offset1:2
	ds_read2_b64 v[156:159], v251 offset0:0 offset1:2
	ds_read2_b64 v[160:163], v201 offset0:4 offset1:6
	ds_read2_b64 v[164:167], v251 offset0:4 offset1:6
	s_waitcnt lgkmcnt(0)
	v_mfma_f32_32x32x16_bf16 v[208:223], v[152:155], v[136:139], v[208:223]
	v_mfma_f32_32x32x16_bf16 v[224:239], v[156:159], v[136:139], v[224:239]
	v_mfma_f32_32x32x16_bf16 v[208:223], v[160:163], v[140:143], v[208:223]
	v_mfma_f32_32x32x16_bf16 v[224:239], v[164:167], v[140:143], v[224:239]
	s_nop 7
	s_nop 3
	ds_write_b128 v205, v[208:211]
	ds_write_b128 v205, v[212:215] offset:32
	ds_write_b128 v205, v[216:219] offset:64
	ds_write_b128 v205, v[220:223] offset:96
	ds_write_b128 v205, v[224:227] offset:128
	ds_write_b128 v205, v[228:231] offset:160
	ds_write_b128 v205, v[232:235] offset:192
	ds_write_b128 v205, v[236:239] offset:224
	s_waitcnt lgkmcnt(0)
	ds_read_b128 v[208:211], v204
	ds_read_b128 v[212:215], v204 offset:1088
	ds_read_b128 v[216:219], v204 offset:2176
	ds_read_b128 v[220:223], v204 offset:3264
	ds_read_b128 v[224:227], v204 offset:4352
	ds_read_b128 v[228:231], v204 offset:5440
	ds_read_b128 v[232:235], v204 offset:6528
	ds_read_b128 v[236:239], v204 offset:7616
	s_waitcnt lgkmcnt(0)
	global_store_dwordx4 v241, v[208:211], s[56:57]
	v_add_u32_e32 v252, 0x2000, v241
	global_store_dwordx4 v252, v[212:215], s[56:57]
	v_add_u32_e32 v252, 0x4000, v241
	global_store_dwordx4 v252, v[216:219], s[56:57]
	v_add_u32_e32 v252, 0x6000, v241
	global_store_dwordx4 v252, v[220:223], s[56:57]
	v_add_u32_e32 v252, 0x8000, v241
	global_store_dwordx4 v252, v[224:227], s[56:57]
	v_add_u32_e32 v252, 0xa000, v241
	global_store_dwordx4 v252, v[228:231], s[56:57]
	v_add_u32_e32 v252, 0xc000, v241
	global_store_dwordx4 v252, v[232:235], s[56:57]
	v_add_u32_e32 v252, 0xe000, v241
	global_store_dwordx4 v252, v[236:239], s[56:57]
	s_mov_b64 exec, 0xffffffff
	global_store_dword v240, v246, s[58:59]
	global_store_dword v240, v248, s[60:61]
	s_mov_b64 exec, -1
	s_lshl_b32 s99, s33, 3
	s_add_i32 s98, s98, s99
	s_cmpk_lt_i32 s98, 0x2000
	s_cbranch_scc1 .Ldil_p0L0_loop
	s_waitcnt lgkmcnt(0)
	s_branch .LBB0_348

.LBB0_410:
	s_mov_b64 exec, -1
	s_load_dwordx2 s[100:101], s[0:1], 0xf0
	s_mov_b32 s98, s94
	v_and_b32_e32 v128, 31, v206
	v_bfe_u32 v249, v206, 5, 1
	v_lshlrev_b32_e32 v129, 4, v249
	v_lshlrev_b32_e32 v250, 2, v249
	v_sub_u32_e32 v130, v128, v250
	v_mov_b32_e32 v131, 0xf149f2ca
	v_and_b32_e32 v133, 7, v206
	v_lshlrev_b32_e32 v133, 4, v133
	v_and_b32_e32 v134, 15, v206
	v_lshlrev_b32_e32 v134, 4, v134
	v_lshrrev_b32_e32 v251, 6, v206
	v_lshlrev_b32_e32 v251, 14, v251
	v_mul_u32_u24_e32 v252, 0x240, v249
	v_lshl_add_u32 v200, v128, 1, v252
	v_add_u32_e32 v200, v200, v251
	v_mul_u32_u24_e32 v252, 72, v128
	v_lshl_add_u32 v201, v249, 3, v252
	v_add_u32_e32 v201, v201, v251
	v_bfe_u32 v252, v206, 3, 3
	v_mul_u32_u24_e32 v252, 144, v252
	v_add3_u32 v202, v252, v133, v251
	v_add_u32_e32 v202, 4608, v202
	v_mul_u32_u24_e32 v252, 144, v128
	v_add3_u32 v203, v252, v129, v251
	v_add_u32_e32 v203, 4608, v203
	v_bfe_u32 v252, v206, 4, 2
	v_mul_u32_u24_e32 v252, 272, v252
	v_add3_u32 v204, v252, v134, v251
	v_add_u32_e32 v204, 4608, v204
	v_mul_u32_u24_e32 v252, 272, v128
	v_add3_u32 v205, v252, v129, v251
	v_add_u32_e32 v205, 4608, v205
	s_waitcnt lgkmcnt(0)
.Ldil_p1L0_loop:
	s_and_b32 s4, s98, 31
	s_bfe_u32 s5, s98, 0x20005
	s_lshr_b32 s6, s98, 10
	s_and_b32 s7, s98, 0x380
	s_lshl_b32 s99, s6, 12
	s_add_u32 s8, s99, s5
	s_sub_u32 s9, 4, s4
	s_max_i32 s9, s9, 0
	s_lshl_b32 s4, s4, 5
	v_add_u32_e32 v135, s4, v128
	s_lshl_b32 s99, s8, 10
	s_add_u32 s99, s99, s7
	s_add_u32 s64, s99, 0x16000000
	s_add_u32 s64, s100, s64
	s_addc_u32 s65, s101, 0
	s_add_u32 s72, s64, 0x2000000
	s_addc_u32 s73, s65, 0
	s_add_u32 s52, s72, 0x2000000
	s_addc_u32 s53, s73, 0
	s_add_u32 s66, s64, 0x8000
	s_addc_u32 s67, s65, 0
	s_add_u32 s74, s72, 0x8000
	s_addc_u32 s75, s73, 0
	s_add_u32 s68, s66, 0x8000
	s_addc_u32 s69, s67, 0
	s_add_u32 s76, s74, 0x8000
	s_addc_u32 s77, s75, 0
	s_add_u32 s70, s68, 0x8000
	s_addc_u32 s71, s69, 0
	s_add_u32 s78, s76, 0x8000
	s_addc_u32 s79, s77, 0
	v_bfe_u32 v249, v206, 3, 3
	v_add_u32_e32 v249, s4, v249
	v_lshl_add_u32 v250, v249, 12, v133
	global_load_dwordx4 v[152:155], v250, s[64:65]
	global_load_dwordx4 v[156:159], v250, s[66:67]
	global_load_dwordx4 v[160:163], v250, s[68:69]
	global_load_dwordx4 v[164:167], v250, s[70:71]
	s_max_u32 s99, s9, 0
	s_lshl_b32 s99, s99, 5
	s_addk_i32 s99, 0xff80
	v_add_u32_e32 v250, s99, v249
	v_lshl_add_u32 v250, v250, 12, v133
	global_load_dwordx4 v[0:3], v250, s[72:73]
	global_load_dwordx4 v[4:7], v250, s[74:75]
	global_load_dwordx4 v[8:11], v250, s[76:77]
	global_load_dwordx4 v[12:15], v250, s[78:79]
	s_max_u32 s99, s9, 1
	s_lshl_b32 s99, s99, 5
	s_addk_i32 s99, 0xff80
	v_add_u32_e32 v250, s99, v249
	v_lshl_add_u32 v250, v250, 12, v133
	global_load_dwordx4 v[16:19], v250, s[72:73]
	global_load_dwordx4 v[20:23], v250, s[74:75]
	global_load_dwordx4 v[24:27], v250, s[76:77]
	global_load_dwordx4 v[28:31], v250, s[78:79]
	s_max_u32 s99, s9, 2
	s_lshl_b32 s99, s99, 5
	s_addk_i32 s99, 0xff80
	v_add_u32_e32 v250, s99, v249
	v_lshl_add_u32 v250, v250, 12, v133
	global_load_dwordx4 v[32:35], v250, s[72:73]
	global_load_dwordx4 v[36:39], v250, s[74:75]
	global_load_dwordx4 v[40:43], v250, s[76:77]
	global_load_dwordx4 v[44:47], v250, s[78:79]
	s_max_u32 s99, s9, 3
	s_lshl_b32 s99, s99, 5
	s_addk_i32 s99, 0xff80
	v_add_u32_e32 v250, s99, v249
	v_lshl_add_u32 v250, v250, 12, v133
	global_load_dwordx4 v[48:51], v250, s[72:73]
	global_load_dwordx4 v[52:55], v250, s[74:75]
	global_load_dwordx4 v[56:59], v250, s[76:77]
	global_load_dwordx4 v[60:63], v250, s[78:79]
	s_max_u32 s99, s9, 4
	s_lshl_b32 s99, s99, 5
	s_addk_i32 s99, 0xff80
	v_add_u32_e32 v250, s99, v249
	v_lshl_add_u32 v250, v250, 12, v133
	global_load_dwordx4 v[64:67], v250, s[72:73]
	global_load_dwordx4 v[68:71], v250, s[74:75]
	global_load_dwordx4 v[72:75], v250, s[76:77]
	global_load_dwordx4 v[76:79], v250, s[78:79]
	s_lshl_b32 s99, s8, 5
	s_lshr_b32 s58, s7, 5
	s_add_u32 s99, s99, s58
	s_add_u32 s99, s99, 0x400000
	s_add_u32 s58, s100, s99
	s_addc_u32 s59, s101, 0
	s_add_u32 s60, s58, 0x100000
	s_addc_u32 s61, s59, 0
	v_lshlrev_b32_e32 v240, 7, v135
	s_lshl_b32 s99, s8, 11
	s_lshl_b32 s56, s7, 1
	s_add_u32 s99, s99, s56
	s_add_u32 s99, s99, 0x8000000
	s_add_u32 s56, s100, s99
	s_addc_u32 s57, s101, 0
	v_bfe_u32 v251, v206, 4, 2
	v_add_u32_e32 v251, s4, v251
	v_lshl_add_u32 v241, v251, 13, v134
	global_load_dword v244, v240, s[58:59]
	global_load_dword v245, v240, s[60:61]
	global_load_dwordx4 v[208:211], v241, s[56:57]
	v_add_u32_e32 v252, 0x8000, v241
	global_load_dwordx4 v[212:215], v252, s[56:57]
	v_add_u32_e32 v252, 0x10000, v241
	global_load_dwordx4 v[216:219], v252, s[56:57]
	v_add_u32_e32 v252, 0x18000, v241
	global_load_dwordx4 v[220:223], v252, s[56:57]
	v_add_u32_e32 v252, 0x20000, v241
	global_load_dwordx4 v[224:227], v252, s[56:57]
	v_add_u32_e32 v252, 0x28000, v241
	global_load_dwordx4 v[228:231], v252, s[56:57]
	v_add_u32_e32 v252, 0x30000, v241
	global_load_dwordx4 v[232:235], v252, s[56:57]
	v_add_u32_e32 v252, 0x38000, v241
	global_load_dwordx4 v[236:239], v252, s[56:57]
	v_mov_b32_e32 v243, v131
	s_waitcnt vmcnt(30)
	ds_write_b128 v202, v[152:155]
	ds_write_b128 v202, v[156:159] offset:1152
	ds_write_b128 v202, v[160:163] offset:2304
	ds_write_b128 v202, v[164:167] offset:3456
	s_waitcnt lgkmcnt(0)
	ds_read_b128 v[136:139], v203
	ds_read_b128 v[140:143], v203 offset:32
	ds_read_b128 v[144:147], v203 offset:64
	ds_read_b128 v[148:151], v203 offset:96
	s_cmp_gt_u32 s9, 0
	s_cbranch_scc1 .Ldil_p1L0_kskip0
	s_waitcnt vmcnt(26)
	s_waitcnt lgkmcnt(0)
	ds_write_b128 v202, v[0:3]
	ds_write_b128 v202, v[4:7] offset:1152
	ds_write_b128 v202, v[8:11] offset:2304
	ds_write_b128 v202, v[12:15] offset:3456
	s_waitcnt lgkmcnt(0)
	s_max_u32 s99, s9, 0
	s_lshl_b32 s99, s99, 5
	s_addk_i32 s99, 0xff80
	v_add_u32_e32 v250, s99, v135
	v_lshl_add_u32 v250, v250, 12, v129
	global_load_dwordx4 v[0:3], v250, s[52:53]
	global_load_dwordx4 v[4:7], v250, s[52:53] offset:32
	global_load_dwordx4 v[8:11], v250, s[52:53] offset:64
	global_load_dwordx4 v[12:15], v250, s[52:53] offset:96
	ds_read_b128 v[152:155], v203
	ds_read_b128 v[156:159], v203 offset:32
	ds_read_b128 v[160:163], v203 offset:64
	ds_read_b128 v[164:167], v203 offset:96
	s_waitcnt lgkmcnt(0)
	v_mfma_f32_32x32x16_bf16 v[80:95], v[152:155], v[136:139], 0
	v_mfma_f32_32x32x16_bf16 v[80:95], v[156:159], v[140:143], v[80:95]
	v_mfma_f32_32x32x16_bf16 v[80:95], v[160:163], v[144:147], v[80:95]
	v_mfma_f32_32x32x16_bf16 v[80:95], v[164:167], v[148:151], v[80:95]
	s_nop 7
	s_nop 3
	v_cmp_gt_i32_e64 s[34:35], v130, 0
	v_cmp_gt_i32_e64 s[36:37], v130, 1
	v_cmp_gt_i32_e64 s[38:39], v130, 2
	v_cmp_gt_i32_e64 s[40:41], v130, 3
	v_cndmask_b32_e64 v80, v80, v131, s[34:35]
	v_cndmask_b32_e64 v81, v81, v131, s[36:37]
	v_cndmask_b32_e64 v82, v82, v131, s[38:39]
	v_cndmask_b32_e64 v83, v83, v131, s[40:41]
	v_cmp_gt_i32_e64 s[34:35], v130, 8
	v_cmp_gt_i32_e64 s[36:37], v130, 9
	v_cmp_gt_i32_e64 s[38:39], v130, 10
	v_cmp_gt_i32_e64 s[40:41], v130, 11
	v_cndmask_b32_e64 v84, v84, v131, s[34:35]
	v_cndmask_b32_e64 v85, v85, v131, s[36:37]
	v_cndmask_b32_e64 v86, v86, v131, s[38:39]
	v_cndmask_b32_e64 v87, v87, v131, s[40:41]
	v_cmp_gt_i32_e64 s[34:35], v130, 16
	v_cmp_gt_i32_e64 s[36:37], v130, 17
	v_cmp_gt_i32_e64 s[38:39], v130, 18
	v_cmp_gt_i32_e64 s[40:41], v130, 19
	v_cndmask_b32_e64 v88, v88, v131, s[34:35]
	v_cndmask_b32_e64 v89, v89, v131, s[36:37]
	v_cndmask_b32_e64 v90, v90, v131, s[38:39]
	v_cndmask_b32_e64 v91, v91, v131, s[40:41]
	v_cmp_gt_i32_e64 s[34:35], v130, 24
	v_cmp_gt_i32_e64 s[36:37], v130, 25
	v_cmp_gt_i32_e64 s[38:39], v130, 26
	v_cmp_gt_i32_e64 s[40:41], v130, 27
	v_cndmask_b32_e64 v92, v92, v131, s[34:35]
	v_cndmask_b32_e64 v93, v93, v131, s[36:37]
	v_cndmask_b32_e64 v94, v94, v131, s[38:39]
	v_cndmask_b32_e64 v95, v95, v131, s[40:41]
	v_max3_f32 v243, v243, v80, v81
	v_max3_f32 v243, v243, v82, v83
	v_max3_f32 v243, v243, v84, v85
	v_max3_f32 v243, v243, v86, v87
	v_max3_f32 v243, v243, v88, v89
	v_max3_f32 v243, v243, v90, v91
	v_max3_f32 v243, v243, v92, v93
	v_max3_f32 v243, v243, v94, v95
	s_branch .Ldil_p1L0_kdone0
.Ldil_p1L0_kskip0:
	s_max_u32 s99, s9, 0
	s_lshl_b32 s99, s99, 5
	s_addk_i32 s99, 0xff80
	v_add_u32_e32 v250, s99, v135
	v_lshl_add_u32 v250, v250, 12, v129
	global_load_dwordx4 v[0:3], v250, s[52:53]
	global_load_dwordx4 v[4:7], v250, s[52:53] offset:32
	global_load_dwordx4 v[8:11], v250, s[52:53] offset:64
	global_load_dwordx4 v[12:15], v250, s[52:53] offset:96
.Ldil_p1L0_kdone0:
	s_cmp_gt_u32 s9, 1
	s_cbranch_scc1 .Ldil_p1L0_kskip1
	s_waitcnt vmcnt(26)
	s_waitcnt lgkmcnt(0)
	ds_write_b128 v202, v[16:19]
	ds_write_b128 v202, v[20:23] offset:1152
	ds_write_b128 v202, v[24:27] offset:2304
	ds_write_b128 v202, v[28:31] offset:3456
	s_waitcnt lgkmcnt(0)
	s_max_u32 s99, s9, 1
	s_lshl_b32 s99, s99, 5
	s_addk_i32 s99, 0xff80
	v_add_u32_e32 v250, s99, v135
	v_lshl_add_u32 v250, v250, 12, v129
	global_load_dwordx4 v[16:19], v250, s[52:53]
	global_load_dwordx4 v[20:23], v250, s[52:53] offset:32
	global_load_dwordx4 v[24:27], v250, s[52:53] offset:64
	global_load_dwordx4 v[28:31], v250, s[52:53] offset:96
	ds_read_b128 v[152:155], v203
	ds_read_b128 v[156:159], v203 offset:32
	ds_read_b128 v[160:163], v203 offset:64
	ds_read_b128 v[164:167], v203 offset:96
	s_waitcnt lgkmcnt(0)
	v_mfma_f32_32x32x16_bf16 v[96:111], v[152:155], v[136:139], 0
	v_mfma_f32_32x32x16_bf16 v[96:111], v[156:159], v[140:143], v[96:111]
	v_mfma_f32_32x32x16_bf16 v[96:111], v[160:163], v[144:147], v[96:111]
	v_mfma_f32_32x32x16_bf16 v[96:111], v[164:167], v[148:151], v[96:111]
	s_nop 7
	s_nop 3
	v_max3_f32 v243, v243, v96, v97
	v_max3_f32 v243, v243, v98, v99
	v_max3_f32 v243, v243, v100, v101
	v_max3_f32 v243, v243, v102, v103
	v_max3_f32 v243, v243, v104, v105
	v_max3_f32 v243, v243, v106, v107
	v_max3_f32 v243, v243, v108, v109
	v_max3_f32 v243, v243, v110, v111
	s_branch .Ldil_p1L0_kdone1
.Ldil_p1L0_kskip1:
	s_max_u32 s99, s9, 1
	s_lshl_b32 s99, s99, 5
	s_addk_i32 s99, 0xff80
	v_add_u32_e32 v250, s99, v135
	v_lshl_add_u32 v250, v250, 12, v129
	global_load_dwordx4 v[16:19], v250, s[52:53]
	global_load_dwordx4 v[20:23], v250, s[52:53] offset:32
	global_load_dwordx4 v[24:27], v250, s[52:53] offset:64
	global_load_dwordx4 v[28:31], v250, s[52:53] offset:96
.Ldil_p1L0_kdone1:
	s_cmp_gt_u32 s9, 2
	s_cbranch_scc1 .Ldil_p1L0_kskip2
	s_waitcnt vmcnt(26)
	s_waitcnt lgkmcnt(0)
	ds_write_b128 v202, v[32:35]
	ds_write_b128 v202, v[36:39] offset:1152
	ds_write_b128 v202, v[40:43] offset:2304
	ds_write_b128 v202, v[44:47] offset:3456
	s_waitcnt lgkmcnt(0)
	s_max_u32 s99, s9, 2
	s_lshl_b32 s99, s99, 5
	s_addk_i32 s99, 0xff80
	v_add_u32_e32 v250, s99, v135
	v_lshl_add_u32 v250, v250, 12, v129
	global_load_dwordx4 v[32:35], v250, s[52:53]
	global_load_dwordx4 v[36:39], v250, s[52:53] offset:32
	global_load_dwordx4 v[40:43], v250, s[52:53] offset:64
	global_load_dwordx4 v[44:47], v250, s[52:53] offset:96
	ds_read_b128 v[152:155], v203
	ds_read_b128 v[156:159], v203 offset:32
	ds_read_b128 v[160:163], v203 offset:64
	ds_read_b128 v[164:167], v203 offset:96
	s_waitcnt lgkmcnt(0)
	v_mfma_f32_32x32x16_bf16 v[112:127], v[152:155], v[136:139], 0
	v_mfma_f32_32x32x16_bf16 v[112:127], v[156:159], v[140:143], v[112:127]
	v_mfma_f32_32x32x16_bf16 v[112:127], v[160:163], v[144:147], v[112:127]
	v_mfma_f32_32x32x16_bf16 v[112:127], v[164:167], v[148:151], v[112:127]
	s_nop 7
	s_nop 3
	v_max3_f32 v243, v243, v112, v113
	v_max3_f32 v243, v243, v114, v115
	v_max3_f32 v243, v243, v116, v117
	v_max3_f32 v243, v243, v118, v119
	v_max3_f32 v243, v243, v120, v121
	v_max3_f32 v243, v243, v122, v123
	v_max3_f32 v243, v243, v124, v125
	v_max3_f32 v243, v243, v126, v127
	s_branch .Ldil_p1L0_kdone2
.Ldil_p1L0_kskip2:
	s_max_u32 s99, s9, 2
	s_lshl_b32 s99, s99, 5
	s_addk_i32 s99, 0xff80
	v_add_u32_e32 v250, s99, v135
	v_lshl_add_u32 v250, v250, 12, v129
	global_load_dwordx4 v[32:35], v250, s[52:53]
	global_load_dwordx4 v[36:39], v250, s[52:53] offset:32
	global_load_dwordx4 v[40:43], v250, s[52:53] offset:64
	global_load_dwordx4 v[44:47], v250, s[52:53] offset:96
.Ldil_p1L0_kdone2:
	s_cmp_gt_u32 s9, 3
	s_cbranch_scc1 .Ldil_p1L0_kskip3
	s_waitcnt vmcnt(26)
	s_waitcnt lgkmcnt(0)
	ds_write_b128 v202, v[48:51]
	ds_write_b128 v202, v[52:55] offset:1152
	ds_write_b128 v202, v[56:59] offset:2304
	ds_write_b128 v202, v[60:63] offset:3456
	s_waitcnt lgkmcnt(0)
	s_max_u32 s99, s9, 3
	s_lshl_b32 s99, s99, 5
	s_addk_i32 s99, 0xff80
	v_add_u32_e32 v250, s99, v135
	v_lshl_add_u32 v250, v250, 12, v129
	global_load_dwordx4 v[48:51], v250, s[52:53]
	global_load_dwordx4 v[52:55], v250, s[52:53] offset:32
	global_load_dwordx4 v[56:59], v250, s[52:53] offset:64
	global_load_dwordx4 v[60:63], v250, s[52:53] offset:96
	ds_read_b128 v[152:155], v203
	ds_read_b128 v[156:159], v203 offset:32
	ds_read_b128 v[160:163], v203 offset:64
	ds_read_b128 v[164:167], v203 offset:96
	s_waitcnt lgkmcnt(0)
	v_mfma_f32_32x32x16_bf16 v[168:183], v[152:155], v[136:139], 0
	v_mfma_f32_32x32x16_bf16 v[168:183], v[156:159], v[140:143], v[168:183]
	v_mfma_f32_32x32x16_bf16 v[168:183], v[160:163], v[144:147], v[168:183]
	v_mfma_f32_32x32x16_bf16 v[168:183], v[164:167], v[148:151], v[168:183]
	s_nop 7
	s_nop 3
	v_max3_f32 v243, v243, v168, v169
	v_max3_f32 v243, v243, v170, v171
	v_max3_f32 v243, v243, v172, v173
	v_max3_f32 v243, v243, v174, v175
	v_max3_f32 v243, v243, v176, v177
	v_max3_f32 v243, v243, v178, v179
	v_max3_f32 v243, v243, v180, v181
	v_max3_f32 v243, v243, v182, v183
	s_branch .Ldil_p1L0_kdone3
.Ldil_p1L0_kskip3:
	s_max_u32 s99, s9, 3
	s_lshl_b32 s99, s99, 5
	s_addk_i32 s99, 0xff80
	v_add_u32_e32 v250, s99, v135
	v_lshl_add_u32 v250, v250, 12, v129
	global_load_dwordx4 v[48:51], v250, s[52:53]
	global_load_dwordx4 v[52:55], v250, s[52:53] offset:32
	global_load_dwordx4 v[56:59], v250, s[52:53] offset:64
	global_load_dwordx4 v[60:63], v250, s[52:53] offset:96
.Ldil_p1L0_kdone3:
	s_waitcnt vmcnt(26)
	s_waitcnt lgkmcnt(0)
	ds_write_b128 v202, v[64:67]
	ds_write_b128 v202, v[68:71] offset:1152
	ds_write_b128 v202, v[72:75] offset:2304
	ds_write_b128 v202, v[76:79] offset:3456
	s_waitcnt lgkmcnt(0)
	s_max_u32 s99, s9, 4
	s_lshl_b32 s99, s99, 5
	s_addk_i32 s99, 0xff80
	v_add_u32_e32 v250, s99, v135
	v_lshl_add_u32 v250, v250, 12, v129
	global_load_dwordx4 v[64:67], v250, s[52:53]
	global_load_dwordx4 v[68:71], v250, s[52:53] offset:32
	global_load_dwordx4 v[72:75], v250, s[52:53] offset:64
	global_load_dwordx4 v[76:79], v250, s[52:53] offset:96
	ds_read_b128 v[152:155], v203
	ds_read_b128 v[156:159], v203 offset:32
	ds_read_b128 v[160:163], v203 offset:64
	ds_read_b128 v[164:167], v203 offset:96
	s_waitcnt lgkmcnt(0)
	v_mfma_f32_32x32x16_bf16 v[184:199], v[152:155], v[136:139], 0
	v_mfma_f32_32x32x16_bf16 v[184:199], v[156:159], v[140:143], v[184:199]
	v_mfma_f32_32x32x16_bf16 v[184:199], v[160:163], v[144:147], v[184:199]
	v_mfma_f32_32x32x16_bf16 v[184:199], v[164:167], v[148:151], v[184:199]
	s_nop 7
	s_nop 3
	v_cmp_lt_i32_e64 s[34:35], v130, 0
	v_cmp_lt_i32_e64 s[36:37], v130, 1
	v_cmp_lt_i32_e64 s[38:39], v130, 2
	v_cmp_lt_i32_e64 s[40:41], v130, 3
	v_cndmask_b32_e64 v184, v184, v131, s[34:35]
	v_cndmask_b32_e64 v185, v185, v131, s[36:37]
	v_cndmask_b32_e64 v186, v186, v131, s[38:39]
	v_cndmask_b32_e64 v187, v187, v131, s[40:41]
	v_cmp_lt_i32_e64 s[34:35], v130, 8
	v_cmp_lt_i32_e64 s[36:37], v130, 9
	v_cmp_lt_i32_e64 s[38:39], v130, 10
	v_cmp_lt_i32_e64 s[40:41], v130, 11
	v_cndmask_b32_e64 v188, v188, v131, s[34:35]
	v_cndmask_b32_e64 v189, v189, v131, s[36:37]
	v_cndmask_b32_e64 v190, v190, v131, s[38:39]
	v_cndmask_b32_e64 v191, v191, v131, s[40:41]
	v_cmp_lt_i32_e64 s[34:35], v130, 16
	v_cmp_lt_i32_e64 s[36:37], v130, 17
	v_cmp_lt_i32_e64 s[38:39], v130, 18
	v_cmp_lt_i32_e64 s[40:41], v130, 19
	v_cndmask_b32_e64 v192, v192, v131, s[34:35]
	v_cndmask_b32_e64 v193, v193, v131, s[36:37]
	v_cndmask_b32_e64 v194, v194, v131, s[38:39]
	v_cndmask_b32_e64 v195, v195, v131, s[40:41]
	v_cmp_lt_i32_e64 s[34:35], v130, 24
	v_cmp_lt_i32_e64 s[36:37], v130, 25
	v_cmp_lt_i32_e64 s[38:39], v130, 26
	v_cmp_lt_i32_e64 s[40:41], v130, 27
	v_cndmask_b32_e64 v196, v196, v131, s[34:35]
	v_cndmask_b32_e64 v197, v197, v131, s[36:37]
	v_cndmask_b32_e64 v198, v198, v131, s[38:39]
	v_cndmask_b32_e64 v199, v199, v131, s[40:41]
	v_max3_f32 v243, v243, v184, v185
	v_max3_f32 v243, v243, v186, v187
	v_max3_f32 v243, v243, v188, v189
	v_max3_f32 v243, v243, v190, v191
	v_max3_f32 v243, v243, v192, v193
	v_max3_f32 v243, v243, v194, v195
	v_max3_f32 v243, v243, v196, v197
	v_max3_f32 v243, v243, v198, v199
	v_mov_b32_e32 v249, v243
	s_nop 1
	v_permlane32_swap_b32_e32 v243, v249
	s_waitcnt vmcnt(28)
	v_max3_f32 v246, v244, v243, v249
	v_sub_f32_e32 v247, v244, v246
	v_exp_f32_e32 v247, v247
	v_mov_b32_e32 v248, 0
	s_cmp_gt_u32 s9, 0
	s_cbranch_scc1 .Ldil_p1L0_eskip0
	v_sub_f32_e32 v80, v80, v246
	v_sub_f32_e32 v81, v81, v246
	v_exp_f32_e32 v80, v80
	v_sub_f32_e32 v82, v82, v246
	v_exp_f32_e32 v81, v81
	v_add_f32_e32 v248, v248, v80
	v_sub_f32_e32 v83, v83, v246
	v_exp_f32_e32 v82, v82
	v_add_f32_e32 v248, v248, v81
	v_sub_f32_e32 v84, v84, v246
	v_exp_f32_e32 v83, v83
	v_add_f32_e32 v248, v248, v82
	v_sub_f32_e32 v85, v85, v246
	v_exp_f32_e32 v84, v84
	v_add_f32_e32 v248, v248, v83
	v_sub_f32_e32 v86, v86, v246
	v_exp_f32_e32 v85, v85
	v_add_f32_e32 v248, v248, v84
	v_sub_f32_e32 v87, v87, v246
	v_exp_f32_e32 v86, v86
	v_add_f32_e32 v248, v248, v85
	v_sub_f32_e32 v88, v88, v246
	v_exp_f32_e32 v87, v87
	v_add_f32_e32 v248, v248, v86
	v_sub_f32_e32 v89, v89, v246
	v_exp_f32_e32 v88, v88
	v_add_f32_e32 v248, v248, v87
	v_sub_f32_e32 v90, v90, v246
	v_exp_f32_e32 v89, v89
	v_add_f32_e32 v248, v248, v88
	v_sub_f32_e32 v91, v91, v246
	v_exp_f32_e32 v90, v90
	v_add_f32_e32 v248, v248, v89
	v_sub_f32_e32 v92, v92, v246
	v_exp_f32_e32 v91, v91
	v_add_f32_e32 v248, v248, v90
	v_sub_f32_e32 v93, v93, v246
	v_exp_f32_e32 v92, v92
	v_add_f32_e32 v248, v248, v91
	v_sub_f32_e32 v94, v94, v246
	v_exp_f32_e32 v93, v93
	v_add_f32_e32 v248, v248, v92
	v_sub_f32_e32 v95, v95, v246
	v_exp_f32_e32 v94, v94
	v_add_f32_e32 v248, v248, v93
	v_exp_f32_e32 v95, v95
	v_add_f32_e32 v248, v248, v94
	s_nop 0
	v_add_f32_e32 v248, v248, v95

.Ldil_p1L0_eskip3:
	v_sub_f32_e32 v184, v184, v246
	v_sub_f32_e32 v185, v185, v246
	v_exp_f32_e32 v184, v184
	v_sub_f32_e32 v186, v186, v246
	v_exp_f32_e32 v185, v185
	v_add_f32_e32 v248, v248, v184
	v_sub_f32_e32 v187, v187, v246
	v_exp_f32_e32 v186, v186
	v_add_f32_e32 v248, v248, v185
	v_sub_f32_e32 v188, v188, v246
	v_exp_f32_e32 v187, v187
	v_add_f32_e32 v248, v248, v186
	v_sub_f32_e32 v189, v189, v246
	v_exp_f32_e32 v188, v188
	v_add_f32_e32 v248, v248, v187
	v_sub_f32_e32 v190, v190, v246
	v_exp_f32_e32 v189, v189
	v_add_f32_e32 v248, v248, v188
	v_sub_f32_e32 v191, v191, v246
	v_exp_f32_e32 v190, v190
	v_add_f32_e32 v248, v248, v189
	v_sub_f32_e32 v192, v192, v246
	v_exp_f32_e32 v191, v191
	v_add_f32_e32 v248, v248, v190
	v_sub_f32_e32 v193, v193, v246
	v_exp_f32_e32 v192, v192
	v_add_f32_e32 v248, v248, v191
	v_sub_f32_e32 v194, v194, v246
	v_exp_f32_e32 v193, v193
	v_add_f32_e32 v248, v248, v192
	v_sub_f32_e32 v195, v195, v246
	v_exp_f32_e32 v194, v194
	v_add_f32_e32 v248, v248, v193
	v_sub_f32_e32 v196, v196, v246
	v_exp_f32_e32 v195, v195
	v_add_f32_e32 v248, v248, v194
	v_sub_f32_e32 v197, v197, v246
	v_exp_f32_e32 v196, v196
	v_add_f32_e32 v248, v248, v195
	v_sub_f32_e32 v198, v198, v246
	v_exp_f32_e32 v197, v197
	v_add_f32_e32 v248, v248, v196
	v_sub_f32_e32 v199, v199, v246
	v_exp_f32_e32 v198, v198
	v_add_f32_e32 v248, v248, v197
	v_exp_f32_e32 v199, v199
	v_add_f32_e32 v248, v248, v198
	s_nop 0
	v_add_f32_e32 v248, v248, v199
	v_mov_b32_e32 v249, v248
	s_nop 1
	v_permlane32_swap_b32_e32 v248, v249
	s_nop 1
	v_add_f32_e32 v248, v248, v249
	v_fmac_f32_e32 v248, v245, v247
	s_waitcnt vmcnt(20)
	ds_write_b128 v204, v[208:211]
	ds_write_b128 v204, v[212:215] offset:1088
	ds_write_b128 v204, v[216:219] offset:2176
	ds_write_b128 v204, v[220:223] offset:3264
	ds_write_b128 v204, v[224:227] offset:4352
	ds_write_b128 v204, v[228:231] offset:5440
	ds_write_b128 v204, v[232:235] offset:6528
	ds_write_b128 v204, v[236:239] offset:7616
	s_waitcnt lgkmcnt(0)
	ds_read_b128 v[208:211], v205
	ds_read_b128 v[212:215], v205 offset:32
	ds_read_b128 v[216:219], v205 offset:64
	ds_read_b128 v[220:223], v205 offset:96
	ds_read_b128 v[224:227], v205 offset:128
	ds_read_b128 v[228:231], v205 offset:160
	ds_read_b128 v[232:235], v205 offset:192
	ds_read_b128 v[236:239], v205 offset:224
	s_waitcnt lgkmcnt(0)
	v_mul_f32_e32 v208, v208, v247
	v_mul_f32_e32 v224, v224, v247
	v_mul_f32_e32 v209, v209, v247
	v_mul_f32_e32 v225, v225, v247
	v_mul_f32_e32 v210, v210, v247
	v_mul_f32_e32 v226, v226, v247
	v_mul_f32_e32 v211, v211, v247
	v_mul_f32_e32 v227, v227, v247
	v_mul_f32_e32 v212, v212, v247
	v_mul_f32_e32 v228, v228, v247
	v_mul_f32_e32 v213, v213, v247
	v_mul_f32_e32 v229, v229, v247
	v_mul_f32_e32 v214, v214, v247
	v_mul_f32_e32 v230, v230, v247
	v_mul_f32_e32 v215, v215, v247
	v_mul_f32_e32 v231, v231, v247
	v_mul_f32_e32 v216, v216, v247
	v_mul_f32_e32 v232, v232, v247
	v_mul_f32_e32 v217, v217, v247
	v_mul_f32_e32 v233, v233, v247
	v_mul_f32_e32 v218, v218, v247
	v_mul_f32_e32 v234, v234, v247
	v_mul_f32_e32 v219, v219, v247
	v_mul_f32_e32 v235, v235, v247
	v_mul_f32_e32 v220, v220, v247
	v_mul_f32_e32 v236, v236, v247
	v_mul_f32_e32 v221, v221, v247
	v_mul_f32_e32 v237, v237, v247
	v_mul_f32_e32 v222, v222, v247
	v_mul_f32_e32 v238, v238, v247
	v_mul_f32_e32 v223, v223, v247
	v_mul_f32_e32 v239, v239, v247
	v_add_u32_e32 v251, 2304, v201
	s_cmp_gt_u32 s9, 0
	s_cbranch_scc1 .Ldil_p1L0_pskip0
	s_waitcnt vmcnt(16)
	ds_write_b16 v200, v0
	ds_write_b16_d16_hi v200, v0 offset:72
	ds_write_b16 v200, v1 offset:144
	ds_write_b16_d16_hi v200, v1 offset:216
	ds_write_b16 v200, v2 offset:288
	ds_write_b16_d16_hi v200, v2 offset:360
	ds_write_b16 v200, v3 offset:432
	ds_write_b16_d16_hi v200, v3 offset:504
	ds_write_b16 v200, v4 offset:1152
	ds_write_b16_d16_hi v200, v4 offset:1224
	ds_write_b16 v200, v5 offset:1296
	ds_write_b16_d16_hi v200, v5 offset:1368
	ds_write_b16 v200, v6 offset:1440
	ds_write_b16_d16_hi v200, v6 offset:1512
	ds_write_b16 v200, v7 offset:1584
	ds_write_b16_d16_hi v200, v7 offset:1656
	ds_write_b16 v200, v8 offset:2304
	ds_write_b16_d16_hi v200, v8 offset:2376
	ds_write_b16 v200, v9 offset:2448
	ds_write_b16_d16_hi v200, v9 offset:2520
	ds_write_b16 v200, v10 offset:2592
	ds_write_b16_d16_hi v200, v10 offset:2664
	ds_write_b16 v200, v11 offset:2736
	ds_write_b16_d16_hi v200, v11 offset:2808
	ds_write_b16 v200, v12 offset:3456
	ds_write_b16_d16_hi v200, v12 offset:3528
	ds_write_b16 v200, v13 offset:3600
	ds_write_b16_d16_hi v200, v13 offset:3672
	ds_write_b16 v200, v14 offset:3744
	ds_write_b16_d16_hi v200, v14 offset:3816
	ds_write_b16 v200, v15 offset:3888
	ds_write_b16_d16_hi v200, v15 offset:3960
	v_cvt_pk_bf16_f32 v136, v80, v81
	v_cvt_pk_bf16_f32 v137, v82, v83
	v_cvt_pk_bf16_f32 v138, v84, v85
	v_cvt_pk_bf16_f32 v139, v86, v87
	v_cvt_pk_bf16_f32 v140, v88, v89
	v_cvt_pk_bf16_f32 v141, v90, v91
	v_cvt_pk_bf16_f32 v142, v92, v93
	v_cvt_pk_bf16_f32 v143, v94, v95
	s_waitcnt lgkmcnt(0)
	ds_read2_b64 v[152:155], v201 offset0:0 offset1:2
	ds_read2_b64 v[156:159], v251 offset0:0 offset1:2
	ds_read2_b64 v[160:163], v201 offset0:4 offset1:6
	ds_read2_b64 v[164:167], v251 offset0:4 offset1:6
	s_waitcnt lgkmcnt(0)
	v_mfma_f32_32x32x16_bf16 v[208:223], v[152:155], v[136:139], v[208:223]
	v_mfma_f32_32x32x16_bf16 v[224:239], v[156:159], v[136:139], v[224:239]
	v_mfma_f32_32x32x16_bf16 v[208:223], v[160:163], v[140:143], v[208:223]
	v_mfma_f32_32x32x16_bf16 v[224:239], v[164:167], v[140:143], v[224:239]

.Ldil_p1L0_pskip3:
	s_waitcnt vmcnt(0)
	ds_write_b16 v200, v64
	ds_write_b16_d16_hi v200, v64 offset:72
	ds_write_b16 v200, v65 offset:144
	ds_write_b16_d16_hi v200, v65 offset:216
	ds_write_b16 v200, v66 offset:288
	ds_write_b16_d16_hi v200, v66 offset:360
	ds_write_b16 v200, v67 offset:432
	ds_write_b16_d16_hi v200, v67 offset:504
	ds_write_b16 v200, v68 offset:1152
	ds_write_b16_d16_hi v200, v68 offset:1224
	ds_write_b16 v200, v69 offset:1296
	ds_write_b16_d16_hi v200, v69 offset:1368
	ds_write_b16 v200, v70 offset:1440
	ds_write_b16_d16_hi v200, v70 offset:1512
	ds_write_b16 v200, v71 offset:1584
	ds_write_b16_d16_hi v200, v71 offset:1656
	ds_write_b16 v200, v72 offset:2304
	ds_write_b16_d16_hi v200, v72 offset:2376
	ds_write_b16 v200, v73 offset:2448
	ds_write_b16_d16_hi v200, v73 offset:2520
	ds_write_b16 v200, v74 offset:2592
	ds_write_b16_d16_hi v200, v74 offset:2664
	ds_write_b16 v200, v75 offset:2736
	ds_write_b16_d16_hi v200, v75 offset:2808
	ds_write_b16 v200, v76 offset:3456
	ds_write_b16_d16_hi v200, v76 offset:3528
	ds_write_b16 v200, v77 offset:3600
	ds_write_b16_d16_hi v200, v77 offset:3672
	ds_write_b16 v200, v78 offset:3744
	ds_write_b16_d16_hi v200, v78 offset:3816
	ds_write_b16 v200, v79 offset:3888
	ds_write_b16_d16_hi v200, v79 offset:3960
	v_cvt_pk_bf16_f32 v136, v184, v185
	v_cvt_pk_bf16_f32 v137, v186, v187
	v_cvt_pk_bf16_f32 v138, v188, v189
	v_cvt_pk_bf16_f32 v139, v190, v191
	v_cvt_pk_bf16_f32 v140, v192, v193
	v_cvt_pk_bf16_f32 v141, v194, v195
	v_cvt_pk_bf16_f32 v142, v196, v197
	v_cvt_pk_bf16_f32 v143, v198, v199
	s_waitcnt lgkmcnt(0)
	ds_read2_b64 v[152:155], v201 offset0:0 offset1:2
	ds_read2_b64 v[156:159], v251 offset0:0 offset1:2
	ds_read2_b64 v[160:163], v201 offset0:4 offset1:6
	ds_read2_b64 v[164:167], v251 offset0:4 offset1:6
	s_waitcnt lgkmcnt(0)
	v_mfma_f32_32x32x16_bf16 v[208:223], v[152:155], v[136:139], v[208:223]
	v_mfma_f32_32x32x16_bf16 v[224:239], v[156:159], v[136:139], v[224:239]
	v_mfma_f32_32x32x16_bf16 v[208:223], v[160:163], v[140:143], v[208:223]
	v_mfma_f32_32x32x16_bf16 v[224:239], v[164:167], v[140:143], v[224:239]
	s_nop 7
	s_nop 3
	ds_write_b128 v205, v[208:211]
	ds_write_b128 v205, v[212:215] offset:32
	ds_write_b128 v205, v[216:219] offset:64
	ds_write_b128 v205, v[220:223] offset:96
	ds_write_b128 v205, v[224:227] offset:128
	ds_write_b128 v205, v[228:231] offset:160
	ds_write_b128 v205, v[232:235] offset:192
	ds_write_b128 v205, v[236:239] offset:224
	s_waitcnt lgkmcnt(0)
	ds_read_b128 v[208:211], v204
	ds_read_b128 v[212:215], v204 offset:1088
	ds_read_b128 v[216:219], v204 offset:2176
	ds_read_b128 v[220:223], v204 offset:3264
	ds_read_b128 v[224:227], v204 offset:4352
	ds_read_b128 v[228:231], v204 offset:5440
	ds_read_b128 v[232:235], v204 offset:6528
	ds_read_b128 v[236:239], v204 offset:7616
	s_waitcnt lgkmcnt(0)
	global_store_dwordx4 v241, v[208:211], s[56:57]
	v_add_u32_e32 v252, 0x8000, v241
	global_store_dwordx4 v252, v[212:215], s[56:57]
	v_add_u32_e32 v252, 0x10000, v241
	global_store_dwordx4 v252, v[216:219], s[56:57]
	v_add_u32_e32 v252, 0x18000, v241
	global_store_dwordx4 v252, v[220:223], s[56:57]
	v_add_u32_e32 v252, 0x20000, v241
	global_store_dwordx4 v252, v[224:227], s[56:57]
	v_add_u32_e32 v252, 0x28000, v241
	global_store_dwordx4 v252, v[228:231], s[56:57]
	v_add_u32_e32 v252, 0x30000, v241
	global_store_dwordx4 v252, v[232:235], s[56:57]
	v_add_u32_e32 v252, 0x38000, v241
	global_store_dwordx4 v252, v[236:239], s[56:57]
	s_mov_b64 exec, 0xffffffff
	global_store_dword v240, v246, s[58:59]
	global_store_dword v240, v248, s[60:61]
	s_mov_b64 exec, -1
	s_lshl_b32 s99, s33, 3
	s_add_i32 s98, s98, s99
	s_cmpk_lt_i32 s98, 0x2000
	s_cbranch_scc1 .Ldil_p1L0_loop
	s_waitcnt lgkmcnt(0)
	s_branch .LBB0_443

.LBB0_499:
	s_mov_b64 exec, -1
	s_load_dwordx2 s[100:101], s[0:1], 0xf0
	s_mov_b32 s98, s8
	v_and_b32_e32 v128, 31, v206
	v_bfe_u32 v249, v206, 5, 1
	v_lshlrev_b32_e32 v129, 4, v249
	v_lshlrev_b32_e32 v250, 2, v249
	v_sub_u32_e32 v130, v128, v250
	v_mov_b32_e32 v131, 0xf149f2ca
	v_and_b32_e32 v133, 7, v206
	v_lshlrev_b32_e32 v133, 4, v133
	v_and_b32_e32 v134, 15, v206
	v_lshlrev_b32_e32 v134, 4, v134
	v_lshrrev_b32_e32 v251, 6, v206
	v_lshlrev_b32_e32 v251, 14, v251
	v_mul_u32_u24_e32 v252, 0x240, v249
	v_lshl_add_u32 v200, v128, 1, v252
	v_add_u32_e32 v200, v200, v251
	v_mul_u32_u24_e32 v252, 72, v128
	v_lshl_add_u32 v201, v249, 3, v252
	v_add_u32_e32 v201, v201, v251
	v_bfe_u32 v252, v206, 3, 3
	v_mul_u32_u24_e32 v252, 144, v252
	v_add3_u32 v202, v252, v133, v251
	v_add_u32_e32 v202, 4608, v202
	v_mul_u32_u24_e32 v252, 144, v128
	v_add3_u32 v203, v252, v129, v251
	v_add_u32_e32 v203, 4608, v203
	v_bfe_u32 v252, v206, 4, 2
	v_mul_u32_u24_e32 v252, 272, v252
	v_add3_u32 v204, v252, v134, v251
	v_add_u32_e32 v204, 4608, v204
	v_mul_u32_u24_e32 v252, 272, v128
	v_add3_u32 v205, v252, v129, v251
	v_add_u32_e32 v205, 4608, v205
	s_waitcnt lgkmcnt(0)
.Ldil_p2L0_loop:
	s_and_b32 s4, s98, 7
	s_bfe_u32 s5, s98, 0x40003
	s_lshr_b32 s6, s98, 10
	s_and_b32 s7, s98, 0x380
	s_lshl_b32 s99, s6, 12
	s_add_u32 s8, s99, s5
	s_sub_u32 s9, 4, s4
	s_max_i32 s9, s9, 0
	s_lshl_b32 s4, s4, 5
	v_add_u32_e32 v135, s4, v128
	s_lshl_b32 s99, s8, 10
	s_add_u32 s99, s99, s7
	s_add_u32 s64, s99, 0x16000000
	s_add_u32 s64, s100, s64
	s_addc_u32 s65, s101, 0
	s_add_u32 s72, s64, 0x2000000
	s_addc_u32 s73, s65, 0
	s_add_u32 s52, s72, 0x2000000
	s_addc_u32 s53, s73, 0
	s_add_u32 s66, s64, 0x20000
	s_addc_u32 s67, s65, 0
	s_add_u32 s74, s72, 0x20000
	s_addc_u32 s75, s73, 0
	s_add_u32 s68, s66, 0x20000
	s_addc_u32 s69, s67, 0
	s_add_u32 s76, s74, 0x20000
	s_addc_u32 s77, s75, 0
	s_add_u32 s70, s68, 0x20000
	s_addc_u32 s71, s69, 0
	s_add_u32 s78, s76, 0x20000
	s_addc_u32 s79, s77, 0
	v_bfe_u32 v249, v206, 3, 3
	v_add_u32_e32 v249, s4, v249
	v_lshl_add_u32 v250, v249, 14, v133
	global_load_dwordx4 v[152:155], v250, s[64:65]
	global_load_dwordx4 v[156:159], v250, s[66:67]
	global_load_dwordx4 v[160:163], v250, s[68:69]
	global_load_dwordx4 v[164:167], v250, s[70:71]
	s_max_u32 s99, s9, 0
	s_lshl_b32 s99, s99, 5
	s_addk_i32 s99, 0xff80
	v_add_u32_e32 v250, s99, v249
	v_lshl_add_u32 v250, v250, 14, v133
	global_load_dwordx4 v[0:3], v250, s[72:73]
	global_load_dwordx4 v[4:7], v250, s[74:75]
	global_load_dwordx4 v[8:11], v250, s[76:77]
	global_load_dwordx4 v[12:15], v250, s[78:79]
	s_max_u32 s99, s9, 1
	s_lshl_b32 s99, s99, 5
	s_addk_i32 s99, 0xff80
	v_add_u32_e32 v250, s99, v249
	v_lshl_add_u32 v250, v250, 14, v133
	global_load_dwordx4 v[16:19], v250, s[72:73]
	global_load_dwordx4 v[20:23], v250, s[74:75]
	global_load_dwordx4 v[24:27], v250, s[76:77]
	global_load_dwordx4 v[28:31], v250, s[78:79]
	s_max_u32 s99, s9, 2
	s_lshl_b32 s99, s99, 5
	s_addk_i32 s99, 0xff80
	v_add_u32_e32 v250, s99, v249
	v_lshl_add_u32 v250, v250, 14, v133
	global_load_dwordx4 v[32:35], v250, s[72:73]
	global_load_dwordx4 v[36:39], v250, s[74:75]
	global_load_dwordx4 v[40:43], v250, s[76:77]
	global_load_dwordx4 v[44:47], v250, s[78:79]
	s_max_u32 s99, s9, 3
	s_lshl_b32 s99, s99, 5
	s_addk_i32 s99, 0xff80
	v_add_u32_e32 v250, s99, v249
	v_lshl_add_u32 v250, v250, 14, v133
	global_load_dwordx4 v[48:51], v250, s[72:73]
	global_load_dwordx4 v[52:55], v250, s[74:75]
	global_load_dwordx4 v[56:59], v250, s[76:77]
	global_load_dwordx4 v[60:63], v250, s[78:79]
	s_max_u32 s99, s9, 4
	s_lshl_b32 s99, s99, 5
	s_addk_i32 s99, 0xff80
	v_add_u32_e32 v250, s99, v249
	v_lshl_add_u32 v250, v250, 14, v133
	global_load_dwordx4 v[64:67], v250, s[72:73]
	global_load_dwordx4 v[68:71], v250, s[74:75]
	global_load_dwordx4 v[72:75], v250, s[76:77]
	global_load_dwordx4 v[76:79], v250, s[78:79]
	s_lshl_b32 s99, s8, 5
	s_lshr_b32 s58, s7, 5
	s_add_u32 s99, s99, s58
	s_add_u32 s99, s99, 0x400000
	s_add_u32 s58, s100, s99
	s_addc_u32 s59, s101, 0
	s_add_u32 s60, s58, 0x100000
	s_addc_u32 s61, s59, 0
	v_lshlrev_b32_e32 v240, 9, v135
	s_lshl_b32 s99, s8, 11
	s_lshl_b32 s56, s7, 1
	s_add_u32 s99, s99, s56
	s_add_u32 s99, s99, 0x8000000
	s_add_u32 s56, s100, s99
	s_addc_u32 s57, s101, 0
	v_bfe_u32 v251, v206, 4, 2
	v_add_u32_e32 v251, s4, v251
	v_lshl_add_u32 v241, v251, 15, v134
	global_load_dword v244, v240, s[58:59]
	global_load_dword v245, v240, s[60:61]
	global_load_dwordx4 v[208:211], v241, s[56:57]
	v_add_u32_e32 v252, 0x20000, v241
	global_load_dwordx4 v[212:215], v252, s[56:57]
	v_add_u32_e32 v252, 0x40000, v241
	global_load_dwordx4 v[216:219], v252, s[56:57]
	v_add_u32_e32 v252, 0x60000, v241
	global_load_dwordx4 v[220:223], v252, s[56:57]
	v_add_u32_e32 v252, 0x80000, v241
	global_load_dwordx4 v[224:227], v252, s[56:57]
	v_add_u32_e32 v252, 0xa0000, v241
	global_load_dwordx4 v[228:231], v252, s[56:57]
	v_add_u32_e32 v252, 0xc0000, v241
	global_load_dwordx4 v[232:235], v252, s[56:57]
	v_add_u32_e32 v252, 0xe0000, v241
	global_load_dwordx4 v[236:239], v252, s[56:57]
	s_lshl_b32 s99, s8, 11
	s_add_u32 s99, s99, s7
	s_add_u32 s99, s99, 0xc000400
	s_add_u32 s62, s100, s99
	s_addc_u32 s63, s101, 0
	v_lshl_add_u32 v242, v249, 15, v133
	v_mov_b32_e32 v243, v131
	s_waitcnt vmcnt(30)
	ds_write_b128 v202, v[152:155]
	ds_write_b128 v202, v[156:159] offset:1152
	ds_write_b128 v202, v[160:163] offset:2304
	ds_write_b128 v202, v[164:167] offset:3456
	s_waitcnt lgkmcnt(0)
	ds_read_b128 v[136:139], v203
	ds_read_b128 v[140:143], v203 offset:32
	ds_read_b128 v[144:147], v203 offset:64
	ds_read_b128 v[148:151], v203 offset:96
	s_cmp_gt_u32 s9, 0
	s_cbranch_scc1 .Ldil_p2L0_kskip0
	s_waitcnt vmcnt(26)
	s_waitcnt lgkmcnt(0)
	ds_write_b128 v202, v[0:3]
	ds_write_b128 v202, v[4:7] offset:1152
	ds_write_b128 v202, v[8:11] offset:2304
	ds_write_b128 v202, v[12:15] offset:3456
	s_waitcnt lgkmcnt(0)
	s_max_u32 s99, s9, 0
	s_lshl_b32 s99, s99, 5
	s_addk_i32 s99, 0xff80
	v_add_u32_e32 v250, s99, v135
	v_lshl_add_u32 v250, v250, 14, v129
	global_load_dwordx4 v[0:3], v250, s[52:53]
	global_load_dwordx4 v[4:7], v250, s[52:53] offset:32
	global_load_dwordx4 v[8:11], v250, s[52:53] offset:64
	global_load_dwordx4 v[12:15], v250, s[52:53] offset:96
	ds_read_b128 v[152:155], v203
	ds_read_b128 v[156:159], v203 offset:32
	ds_read_b128 v[160:163], v203 offset:64
	ds_read_b128 v[164:167], v203 offset:96
	s_waitcnt lgkmcnt(0)
	v_mfma_f32_32x32x16_bf16 v[80:95], v[152:155], v[136:139], 0
	v_mfma_f32_32x32x16_bf16 v[80:95], v[156:159], v[140:143], v[80:95]
	v_mfma_f32_32x32x16_bf16 v[80:95], v[160:163], v[144:147], v[80:95]
	v_mfma_f32_32x32x16_bf16 v[80:95], v[164:167], v[148:151], v[80:95]
	s_nop 7
	s_nop 3
	v_cmp_gt_i32_e64 s[34:35], v130, 0
	v_cmp_gt_i32_e64 s[36:37], v130, 1
	v_cmp_gt_i32_e64 s[38:39], v130, 2
	v_cmp_gt_i32_e64 s[40:41], v130, 3
	v_cndmask_b32_e64 v80, v80, v131, s[34:35]
	v_cndmask_b32_e64 v81, v81, v131, s[36:37]
	v_cndmask_b32_e64 v82, v82, v131, s[38:39]
	v_cndmask_b32_e64 v83, v83, v131, s[40:41]
	v_cmp_gt_i32_e64 s[34:35], v130, 8
	v_cmp_gt_i32_e64 s[36:37], v130, 9
	v_cmp_gt_i32_e64 s[38:39], v130, 10
	v_cmp_gt_i32_e64 s[40:41], v130, 11
	v_cndmask_b32_e64 v84, v84, v131, s[34:35]
	v_cndmask_b32_e64 v85, v85, v131, s[36:37]
	v_cndmask_b32_e64 v86, v86, v131, s[38:39]
	v_cndmask_b32_e64 v87, v87, v131, s[40:41]
	v_cmp_gt_i32_e64 s[34:35], v130, 16
	v_cmp_gt_i32_e64 s[36:37], v130, 17
	v_cmp_gt_i32_e64 s[38:39], v130, 18
	v_cmp_gt_i32_e64 s[40:41], v130, 19
	v_cndmask_b32_e64 v88, v88, v131, s[34:35]
	v_cndmask_b32_e64 v89, v89, v131, s[36:37]
	v_cndmask_b32_e64 v90, v90, v131, s[38:39]
	v_cndmask_b32_e64 v91, v91, v131, s[40:41]
	v_cmp_gt_i32_e64 s[34:35], v130, 24
	v_cmp_gt_i32_e64 s[36:37], v130, 25
	v_cmp_gt_i32_e64 s[38:39], v130, 26
	v_cmp_gt_i32_e64 s[40:41], v130, 27
	v_cndmask_b32_e64 v92, v92, v131, s[34:35]
	v_cndmask_b32_e64 v93, v93, v131, s[36:37]
	v_cndmask_b32_e64 v94, v94, v131, s[38:39]
	v_cndmask_b32_e64 v95, v95, v131, s[40:41]
	v_max3_f32 v243, v243, v80, v81
	v_max3_f32 v243, v243, v82, v83
	v_max3_f32 v243, v243, v84, v85
	v_max3_f32 v243, v243, v86, v87
	v_max3_f32 v243, v243, v88, v89
	v_max3_f32 v243, v243, v90, v91
	v_max3_f32 v243, v243, v92, v93
	v_max3_f32 v243, v243, v94, v95
	s_branch .Ldil_p2L0_kdone0
.Ldil_p2L0_kskip0:
	s_max_u32 s99, s9, 0
	s_lshl_b32 s99, s99, 5
	s_addk_i32 s99, 0xff80
	v_add_u32_e32 v250, s99, v135
	v_lshl_add_u32 v250, v250, 14, v129
	global_load_dwordx4 v[0:3], v250, s[52:53]
	global_load_dwordx4 v[4:7], v250, s[52:53] offset:32
	global_load_dwordx4 v[8:11], v250, s[52:53] offset:64
	global_load_dwordx4 v[12:15], v250, s[52:53] offset:96
.Ldil_p2L0_kdone0:
	s_cmp_gt_u32 s9, 1
	s_cbranch_scc1 .Ldil_p2L0_kskip1
	s_waitcnt vmcnt(26)
	s_waitcnt lgkmcnt(0)
	ds_write_b128 v202, v[16:19]
	ds_write_b128 v202, v[20:23] offset:1152
	ds_write_b128 v202, v[24:27] offset:2304
	ds_write_b128 v202, v[28:31] offset:3456
	s_waitcnt lgkmcnt(0)
	s_max_u32 s99, s9, 1
	s_lshl_b32 s99, s99, 5
	s_addk_i32 s99, 0xff80
	v_add_u32_e32 v250, s99, v135
	v_lshl_add_u32 v250, v250, 14, v129
	global_load_dwordx4 v[16:19], v250, s[52:53]
	global_load_dwordx4 v[20:23], v250, s[52:53] offset:32
	global_load_dwordx4 v[24:27], v250, s[52:53] offset:64
	global_load_dwordx4 v[28:31], v250, s[52:53] offset:96
	ds_read_b128 v[152:155], v203
	ds_read_b128 v[156:159], v203 offset:32
	ds_read_b128 v[160:163], v203 offset:64
	ds_read_b128 v[164:167], v203 offset:96
	s_waitcnt lgkmcnt(0)
	v_mfma_f32_32x32x16_bf16 v[96:111], v[152:155], v[136:139], 0
	v_mfma_f32_32x32x16_bf16 v[96:111], v[156:159], v[140:143], v[96:111]
	v_mfma_f32_32x32x16_bf16 v[96:111], v[160:163], v[144:147], v[96:111]
	v_mfma_f32_32x32x16_bf16 v[96:111], v[164:167], v[148:151], v[96:111]
	s_nop 7
	s_nop 3
	v_max3_f32 v243, v243, v96, v97
	v_max3_f32 v243, v243, v98, v99
	v_max3_f32 v243, v243, v100, v101
	v_max3_f32 v243, v243, v102, v103
	v_max3_f32 v243, v243, v104, v105
	v_max3_f32 v243, v243, v106, v107
	v_max3_f32 v243, v243, v108, v109
	v_max3_f32 v243, v243, v110, v111
	s_branch .Ldil_p2L0_kdone1
.Ldil_p2L0_kskip1:
	s_max_u32 s99, s9, 1
	s_lshl_b32 s99, s99, 5
	s_addk_i32 s99, 0xff80
	v_add_u32_e32 v250, s99, v135
	v_lshl_add_u32 v250, v250, 14, v129
	global_load_dwordx4 v[16:19], v250, s[52:53]
	global_load_dwordx4 v[20:23], v250, s[52:53] offset:32
	global_load_dwordx4 v[24:27], v250, s[52:53] offset:64
	global_load_dwordx4 v[28:31], v250, s[52:53] offset:96
.Ldil_p2L0_kdone1:
	s_cmp_gt_u32 s9, 2
	s_cbranch_scc1 .Ldil_p2L0_kskip2
	s_waitcnt vmcnt(26)
	s_waitcnt lgkmcnt(0)
	ds_write_b128 v202, v[32:35]
	ds_write_b128 v202, v[36:39] offset:1152
	ds_write_b128 v202, v[40:43] offset:2304
	ds_write_b128 v202, v[44:47] offset:3456
	s_waitcnt lgkmcnt(0)
	s_max_u32 s99, s9, 2
	s_lshl_b32 s99, s99, 5
	s_addk_i32 s99, 0xff80
	v_add_u32_e32 v250, s99, v135
	v_lshl_add_u32 v250, v250, 14, v129
	global_load_dwordx4 v[32:35], v250, s[52:53]
	global_load_dwordx4 v[36:39], v250, s[52:53] offset:32
	global_load_dwordx4 v[40:43], v250, s[52:53] offset:64
	global_load_dwordx4 v[44:47], v250, s[52:53] offset:96
	ds_read_b128 v[152:155], v203
	ds_read_b128 v[156:159], v203 offset:32
	ds_read_b128 v[160:163], v203 offset:64
	ds_read_b128 v[164:167], v203 offset:96
	s_waitcnt lgkmcnt(0)
	v_mfma_f32_32x32x16_bf16 v[112:127], v[152:155], v[136:139], 0
	v_mfma_f32_32x32x16_bf16 v[112:127], v[156:159], v[140:143], v[112:127]
	v_mfma_f32_32x32x16_bf16 v[112:127], v[160:163], v[144:147], v[112:127]
	v_mfma_f32_32x32x16_bf16 v[112:127], v[164:167], v[148:151], v[112:127]
	s_nop 7
	s_nop 3
	v_max3_f32 v243, v243, v112, v113
	v_max3_f32 v243, v243, v114, v115
	v_max3_f32 v243, v243, v116, v117
	v_max3_f32 v243, v243, v118, v119
	v_max3_f32 v243, v243, v120, v121
	v_max3_f32 v243, v243, v122, v123
	v_max3_f32 v243, v243, v124, v125
	v_max3_f32 v243, v243, v126, v127
	s_branch .Ldil_p2L0_kdone2
.Ldil_p2L0_kskip2:
	s_max_u32 s99, s9, 2
	s_lshl_b32 s99, s99, 5
	s_addk_i32 s99, 0xff80
	v_add_u32_e32 v250, s99, v135
	v_lshl_add_u32 v250, v250, 14, v129
	global_load_dwordx4 v[32:35], v250, s[52:53]
	global_load_dwordx4 v[36:39], v250, s[52:53] offset:32
	global_load_dwordx4 v[40:43], v250, s[52:53] offset:64
	global_load_dwordx4 v[44:47], v250, s[52:53] offset:96
.Ldil_p2L0_kdone2:
	s_cmp_gt_u32 s9, 3
	s_cbranch_scc1 .Ldil_p2L0_kskip3
	s_waitcnt vmcnt(26)
	s_waitcnt lgkmcnt(0)
	ds_write_b128 v202, v[48:51]
	ds_write_b128 v202, v[52:55] offset:1152
	ds_write_b128 v202, v[56:59] offset:2304
	ds_write_b128 v202, v[60:63] offset:3456
	s_waitcnt lgkmcnt(0)
	s_max_u32 s99, s9, 3
	s_lshl_b32 s99, s99, 5
	s_addk_i32 s99, 0xff80
	v_add_u32_e32 v250, s99, v135
	v_lshl_add_u32 v250, v250, 14, v129
	global_load_dwordx4 v[48:51], v250, s[52:53]
	global_load_dwordx4 v[52:55], v250, s[52:53] offset:32
	global_load_dwordx4 v[56:59], v250, s[52:53] offset:64
	global_load_dwordx4 v[60:63], v250, s[52:53] offset:96
	ds_read_b128 v[152:155], v203
	ds_read_b128 v[156:159], v203 offset:32
	ds_read_b128 v[160:163], v203 offset:64
	ds_read_b128 v[164:167], v203 offset:96
	s_waitcnt lgkmcnt(0)
	v_mfma_f32_32x32x16_bf16 v[168:183], v[152:155], v[136:139], 0
	v_mfma_f32_32x32x16_bf16 v[168:183], v[156:159], v[140:143], v[168:183]
	v_mfma_f32_32x32x16_bf16 v[168:183], v[160:163], v[144:147], v[168:183]
	v_mfma_f32_32x32x16_bf16 v[168:183], v[164:167], v[148:151], v[168:183]
	s_nop 7
	s_nop 3
	v_max3_f32 v243, v243, v168, v169
	v_max3_f32 v243, v243, v170, v171
	v_max3_f32 v243, v243, v172, v173
	v_max3_f32 v243, v243, v174, v175
	v_max3_f32 v243, v243, v176, v177
	v_max3_f32 v243, v243, v178, v179
	v_max3_f32 v243, v243, v180, v181
	v_max3_f32 v243, v243, v182, v183
	s_branch .Ldil_p2L0_kdone3
.Ldil_p2L0_kskip3:
	s_max_u32 s99, s9, 3
	s_lshl_b32 s99, s99, 5
	s_addk_i32 s99, 0xff80
	v_add_u32_e32 v250, s99, v135
	v_lshl_add_u32 v250, v250, 14, v129
	global_load_dwordx4 v[48:51], v250, s[52:53]
	global_load_dwordx4 v[52:55], v250, s[52:53] offset:32
	global_load_dwordx4 v[56:59], v250, s[52:53] offset:64
	global_load_dwordx4 v[60:63], v250, s[52:53] offset:96
.Ldil_p2L0_kdone3:
	s_waitcnt vmcnt(26)
	s_waitcnt lgkmcnt(0)
	ds_write_b128 v202, v[64:67]
	ds_write_b128 v202, v[68:71] offset:1152
	ds_write_b128 v202, v[72:75] offset:2304
	ds_write_b128 v202, v[76:79] offset:3456
	s_waitcnt lgkmcnt(0)
	s_max_u32 s99, s9, 4
	s_lshl_b32 s99, s99, 5
	s_addk_i32 s99, 0xff80
	v_add_u32_e32 v250, s99, v135
	v_lshl_add_u32 v250, v250, 14, v129
	global_load_dwordx4 v[64:67], v250, s[52:53]
	global_load_dwordx4 v[68:71], v250, s[52:53] offset:32
	global_load_dwordx4 v[72:75], v250, s[52:53] offset:64
	global_load_dwordx4 v[76:79], v250, s[52:53] offset:96
	ds_read_b128 v[152:155], v203
	ds_read_b128 v[156:159], v203 offset:32
	ds_read_b128 v[160:163], v203 offset:64
	ds_read_b128 v[164:167], v203 offset:96
	s_waitcnt lgkmcnt(0)
	v_mfma_f32_32x32x16_bf16 v[184:199], v[152:155], v[136:139], 0
	v_mfma_f32_32x32x16_bf16 v[184:199], v[156:159], v[140:143], v[184:199]
	v_mfma_f32_32x32x16_bf16 v[184:199], v[160:163], v[144:147], v[184:199]
	v_mfma_f32_32x32x16_bf16 v[184:199], v[164:167], v[148:151], v[184:199]
	s_nop 7
	s_nop 3
	v_cmp_lt_i32_e64 s[34:35], v130, 0
	v_cmp_lt_i32_e64 s[36:37], v130, 1
	v_cmp_lt_i32_e64 s[38:39], v130, 2
	v_cmp_lt_i32_e64 s[40:41], v130, 3
	v_cndmask_b32_e64 v184, v184, v131, s[34:35]
	v_cndmask_b32_e64 v185, v185, v131, s[36:37]
	v_cndmask_b32_e64 v186, v186, v131, s[38:39]
	v_cndmask_b32_e64 v187, v187, v131, s[40:41]
	v_cmp_lt_i32_e64 s[34:35], v130, 8
	v_cmp_lt_i32_e64 s[36:37], v130, 9
	v_cmp_lt_i32_e64 s[38:39], v130, 10
	v_cmp_lt_i32_e64 s[40:41], v130, 11
	v_cndmask_b32_e64 v188, v188, v131, s[34:35]
	v_cndmask_b32_e64 v189, v189, v131, s[36:37]
	v_cndmask_b32_e64 v190, v190, v131, s[38:39]
	v_cndmask_b32_e64 v191, v191, v131, s[40:41]
	v_cmp_lt_i32_e64 s[34:35], v130, 16
	v_cmp_lt_i32_e64 s[36:37], v130, 17
	v_cmp_lt_i32_e64 s[38:39], v130, 18
	v_cmp_lt_i32_e64 s[40:41], v130, 19
	v_cndmask_b32_e64 v192, v192, v131, s[34:35]
	v_cndmask_b32_e64 v193, v193, v131, s[36:37]
	v_cndmask_b32_e64 v194, v194, v131, s[38:39]
	v_cndmask_b32_e64 v195, v195, v131, s[40:41]
	v_cmp_lt_i32_e64 s[34:35], v130, 24
	v_cmp_lt_i32_e64 s[36:37], v130, 25
	v_cmp_lt_i32_e64 s[38:39], v130, 26
	v_cmp_lt_i32_e64 s[40:41], v130, 27
	v_cndmask_b32_e64 v196, v196, v131, s[34:35]
	v_cndmask_b32_e64 v197, v197, v131, s[36:37]
	v_cndmask_b32_e64 v198, v198, v131, s[38:39]
	v_cndmask_b32_e64 v199, v199, v131, s[40:41]
	v_max3_f32 v243, v243, v184, v185
	v_max3_f32 v243, v243, v186, v187
	v_max3_f32 v243, v243, v188, v189
	v_max3_f32 v243, v243, v190, v191
	v_max3_f32 v243, v243, v192, v193
	v_max3_f32 v243, v243, v194, v195
	v_max3_f32 v243, v243, v196, v197
	v_max3_f32 v243, v243, v198, v199
	v_mov_b32_e32 v249, v243
	s_nop 1
	v_permlane32_swap_b32_e32 v243, v249
	s_waitcnt vmcnt(28)
	v_max3_f32 v246, v244, v243, v249
	v_sub_f32_e32 v247, v244, v246
	v_exp_f32_e32 v247, v247
	v_mov_b32_e32 v248, 0
	s_cmp_gt_u32 s9, 0
	s_cbranch_scc1 .Ldil_p2L0_eskip0
	v_sub_f32_e32 v80, v80, v246
	v_sub_f32_e32 v81, v81, v246
	v_exp_f32_e32 v80, v80
	v_sub_f32_e32 v82, v82, v246
	v_exp_f32_e32 v81, v81
	v_add_f32_e32 v248, v248, v80
	v_sub_f32_e32 v83, v83, v246
	v_exp_f32_e32 v82, v82
	v_add_f32_e32 v248, v248, v81
	v_sub_f32_e32 v84, v84, v246
	v_exp_f32_e32 v83, v83
	v_add_f32_e32 v248, v248, v82
	v_sub_f32_e32 v85, v85, v246
	v_exp_f32_e32 v84, v84
	v_add_f32_e32 v248, v248, v83
	v_sub_f32_e32 v86, v86, v246
	v_exp_f32_e32 v85, v85
	v_add_f32_e32 v248, v248, v84
	v_sub_f32_e32 v87, v87, v246
	v_exp_f32_e32 v86, v86
	v_add_f32_e32 v248, v248, v85
	v_sub_f32_e32 v88, v88, v246
	v_exp_f32_e32 v87, v87
	v_add_f32_e32 v248, v248, v86
	v_sub_f32_e32 v89, v89, v246
	v_exp_f32_e32 v88, v88
	v_add_f32_e32 v248, v248, v87
	v_sub_f32_e32 v90, v90, v246
	v_exp_f32_e32 v89, v89
	v_add_f32_e32 v248, v248, v88
	v_sub_f32_e32 v91, v91, v246
	v_exp_f32_e32 v90, v90
	v_add_f32_e32 v248, v248, v89
	v_sub_f32_e32 v92, v92, v246
	v_exp_f32_e32 v91, v91
	v_add_f32_e32 v248, v248, v90
	v_sub_f32_e32 v93, v93, v246
	v_exp_f32_e32 v92, v92
	v_add_f32_e32 v248, v248, v91
	v_sub_f32_e32 v94, v94, v246
	v_exp_f32_e32 v93, v93
	v_add_f32_e32 v248, v248, v92
	v_sub_f32_e32 v95, v95, v246
	v_exp_f32_e32 v94, v94
	v_add_f32_e32 v248, v248, v93
	v_exp_f32_e32 v95, v95
	v_add_f32_e32 v248, v248, v94
	s_nop 0
	v_add_f32_e32 v248, v248, v95

.Ldil_p2L0_pskip3:
	s_waitcnt vmcnt(0)
	ds_write_b16 v200, v64
	ds_write_b16_d16_hi v200, v64 offset:72
	ds_write_b16 v200, v65 offset:144
	ds_write_b16_d16_hi v200, v65 offset:216
	ds_write_b16 v200, v66 offset:288
	ds_write_b16_d16_hi v200, v66 offset:360
	ds_write_b16 v200, v67 offset:432
	ds_write_b16_d16_hi v200, v67 offset:504
	ds_write_b16 v200, v68 offset:1152
	ds_write_b16_d16_hi v200, v68 offset:1224
	ds_write_b16 v200, v69 offset:1296
	ds_write_b16_d16_hi v200, v69 offset:1368
	ds_write_b16 v200, v70 offset:1440
	ds_write_b16_d16_hi v200, v70 offset:1512
	ds_write_b16 v200, v71 offset:1584
	ds_write_b16_d16_hi v200, v71 offset:1656
	ds_write_b16 v200, v72 offset:2304
	ds_write_b16_d16_hi v200, v72 offset:2376
	ds_write_b16 v200, v73 offset:2448
	ds_write_b16_d16_hi v200, v73 offset:2520
	ds_write_b16 v200, v74 offset:2592
	ds_write_b16_d16_hi v200, v74 offset:2664
	ds_write_b16 v200, v75 offset:2736
	ds_write_b16_d16_hi v200, v75 offset:2808
	ds_write_b16 v200, v76 offset:3456
	ds_write_b16_d16_hi v200, v76 offset:3528
	ds_write_b16 v200, v77 offset:3600
	ds_write_b16_d16_hi v200, v77 offset:3672
	ds_write_b16 v200, v78 offset:3744
	ds_write_b16_d16_hi v200, v78 offset:3816
	ds_write_b16 v200, v79 offset:3888
	ds_write_b16_d16_hi v200, v79 offset:3960
	v_cvt_pk_bf16_f32 v136, v184, v185
	v_cvt_pk_bf16_f32 v137, v186, v187
	v_cvt_pk_bf16_f32 v138, v188, v189
	v_cvt_pk_bf16_f32 v139, v190, v191
	v_cvt_pk_bf16_f32 v140, v192, v193
	v_cvt_pk_bf16_f32 v141, v194, v195
	v_cvt_pk_bf16_f32 v142, v196, v197
	v_cvt_pk_bf16_f32 v143, v198, v199
	s_waitcnt lgkmcnt(0)
	ds_read2_b64 v[152:155], v201 offset0:0 offset1:2
	ds_read2_b64 v[156:159], v251 offset0:0 offset1:2
	ds_read2_b64 v[160:163], v201 offset0:4 offset1:6
	ds_read2_b64 v[164:167], v251 offset0:4 offset1:6
	s_waitcnt lgkmcnt(0)
	v_mfma_f32_32x32x16_bf16 v[208:223], v[152:155], v[136:139], v[208:223]
	v_mfma_f32_32x32x16_bf16 v[224:239], v[156:159], v[136:139], v[224:239]
	v_mfma_f32_32x32x16_bf16 v[208:223], v[160:163], v[140:143], v[208:223]
	v_mfma_f32_32x32x16_bf16 v[224:239], v[164:167], v[140:143], v[224:239]
	v_rcp_f32_e32 v249, v248
	s_nop 0
	v_fma_f32 v250, -v248, v249, 1.0
	v_fmac_f32_e32 v249, v250, v249
	v_lshrrev_b32_e32 v252, 1, v129
	v_sub_u32_e32 v252, v203, v252
	s_nop 5
	v_mul_f32_e32 v208, v208, v249
	v_mul_f32_e32 v209, v209, v249
	v_mul_f32_e32 v210, v210, v249
	v_mul_f32_e32 v211, v211, v249
	v_cvt_pk_bf16_f32 v208, v208, v209
	v_cvt_pk_bf16_f32 v209, v210, v211
	ds_write_b64 v252, v[208:209]
	v_mul_f32_e32 v212, v212, v249
	v_mul_f32_e32 v213, v213, v249
	v_mul_f32_e32 v214, v214, v249
	v_mul_f32_e32 v215, v215, v249
	v_cvt_pk_bf16_f32 v212, v212, v213
	v_cvt_pk_bf16_f32 v213, v214, v215
	ds_write_b64 v252, v[212:213] offset:16
	v_mul_f32_e32 v216, v216, v249
	v_mul_f32_e32 v217, v217, v249
	v_mul_f32_e32 v218, v218, v249
	v_mul_f32_e32 v219, v219, v249
	v_cvt_pk_bf16_f32 v216, v216, v217
	v_cvt_pk_bf16_f32 v217, v218, v219
	ds_write_b64 v252, v[216:217] offset:32
	v_mul_f32_e32 v220, v220, v249
	v_mul_f32_e32 v221, v221, v249
	v_mul_f32_e32 v222, v222, v249
	v_mul_f32_e32 v223, v223, v249
	v_cvt_pk_bf16_f32 v220, v220, v221
	v_cvt_pk_bf16_f32 v221, v222, v223
	ds_write_b64 v252, v[220:221] offset:48
	v_mul_f32_e32 v224, v224, v249
	v_mul_f32_e32 v225, v225, v249
	v_mul_f32_e32 v226, v226, v249
	v_mul_f32_e32 v227, v227, v249
	v_cvt_pk_bf16_f32 v224, v224, v225
	v_cvt_pk_bf16_f32 v225, v226, v227
	ds_write_b64 v252, v[224:225] offset:64
	v_mul_f32_e32 v228, v228, v249
	v_mul_f32_e32 v229, v229, v249
	v_mul_f32_e32 v230, v230, v249
	v_mul_f32_e32 v231, v231, v249
	v_cvt_pk_bf16_f32 v228, v228, v229
	v_cvt_pk_bf16_f32 v229, v230, v231
	ds_write_b64 v252, v[228:229] offset:80
	v_mul_f32_e32 v232, v232, v249
	v_mul_f32_e32 v233, v233, v249
	v_mul_f32_e32 v234, v234, v249
	v_mul_f32_e32 v235, v235, v249
	v_cvt_pk_bf16_f32 v232, v232, v233
	v_cvt_pk_bf16_f32 v233, v234, v235
	ds_write_b64 v252, v[232:233] offset:96
	v_mul_f32_e32 v236, v236, v249
	v_mul_f32_e32 v237, v237, v249
	v_mul_f32_e32 v238, v238, v249
	v_mul_f32_e32 v239, v239, v249
	v_cvt_pk_bf16_f32 v236, v236, v237
	v_cvt_pk_bf16_f32 v237, v238, v239
	ds_write_b64 v252, v[236:237] offset:112
	s_waitcnt lgkmcnt(0)
	ds_read_b128 v[208:211], v202
	ds_read_b128 v[212:215], v202 offset:1152
	ds_read_b128 v[216:219], v202 offset:2304
	ds_read_b128 v[220:223], v202 offset:3456
	s_waitcnt lgkmcnt(0)
	global_store_dwordx4 v242, v[208:211], s[62:63]
	v_add_u32_e32 v250, 0x40000, v242
	global_store_dwordx4 v250, v[212:215], s[62:63]
	v_add_u32_e32 v250, 0x80000, v242
	global_store_dwordx4 v250, v[216:219], s[62:63]
	v_add_u32_e32 v250, 0xc0000, v242
	global_store_dwordx4 v250, v[220:223], s[62:63]
	s_lshl_b32 s99, s33, 3
	s_add_i32 s98, s98, s99
	s_cmpk_lt_i32 s98, 0x2000
	s_cbranch_scc1 .Ldil_p2L0_loop
	s_waitcnt lgkmcnt(0)
	s_branch .LBB0_530
